# row sum-of-squares lane reductions in the four residual-epilogue GEMMs: ds_bpermute xor-16/xor-32 hops replaced by v_permlane16_swap / v_permlane32_swap + add (bitwise-identical sums, no LDS round tri
# speedup vs baseline: 1.0072x; 1.0013x over previous
; __device__ __forceinline__ float bf_lo(unsigned u) { return __uint_as_float(u << 16); }
; __device__ __forceinline__ float bf_hi(unsigned u) { return __uint_as_float(u & 0xffff0000u); }
; __device__ __forceinline__ u32x4 pack8(f32x4 a, f32x4 b) { u32x4 o; o[0] = cvt_pk_bf16(a[0], a[1]); o[1] = cvt_pk_bf16(a[2], a[3]); o[2] = cvt_pk_bf16(b[0], b[1]); o[3] = cvt_pk_bf16(b[2], b[3]); return o; }
;   __device__ __forceinline__ void operator()(const AccT& acc, const Unit& u, int ui, int wr, int wc, int fr, int fq) const {
;     ...
;       u32x4 xh[4][2];
; #pragma unroll
;       for (int m = 0; m < 4; ++m)
; #pragma unroll
;         for (int bj = 0; bj < 2; ++bj)
;           xh[m][bj] = *(const u32x4*)(XB + (size_t)(u.pm * 256 + ai * 128 + wr * 64 + m * 16 + fr) * DM + u.pn * 256 + bj * 128 + wc * 32 + fq * 8);
; #pragma unroll
;       for (int m = 0; m < 4; ++m) {
;         const int row = u.pm * 256 + ai * 128 + wr * 64 + m * 16 + fr; float ss = 0.f;
; #pragma unroll
;         for (int bj = 0; bj < 2; ++bj) {
;           const size_t o = (size_t)row * DM + u.pn * 256 + bj * 128 + wc * 32 + fq * 8;
;           const u32x4 h4 = xh[m][bj];
;           f32x4 y0 = {bf_lo(h4[0]), bf_hi(h4[0]), bf_lo(h4[1]), bf_hi(h4[1])}, y1 = {bf_lo(h4[2]), bf_hi(h4[2]), bf_lo(h4[3]), bf_hi(h4[3])};
;           y0 += acc[ai][bj][m][0] * s; y1 += acc[ai][bj][m][1] * s;
;           *(u32x4*)(XB + o) = pack8(y0, y1);
; #pragma unroll
;           for (int i = 0; i < 4; ++i) ss += y0[i] * y0[i] + y1[i] * y1[i];
;         }
;         ss += __shfl_xor(ss, 16); ss += __shfl_xor(ss, 32);
;         if (fq == 0) RSS[(size_t)row * 16 + u.pn * 4 + wc] = ss;
.Lxa_1:
	v_and_b32_e32 v129, 64, v219
	v_xor_b32_e32 v128, 16, v219
	v_add_u32_e32 v129, 64, v129
	v_cmp_lt_i32_e32 vcc, v128, v129
	s_lshl_b32 s44, s20, 8
	v_lshl_add_u32 v186, s69, 8, v179
	v_cndmask_b32_e32 v128, v219, v128, vcc
	s_ashr_i32 s45, s44, 31
	v_lshlrev_b32_e32 v205, 2, v128
	v_xor_b32_e32 v128, 32, v219
	v_cmp_lt_i32_e32 vcc, v128, v129
	s_lshl_b64 s[34:35], s[44:45], 1
	v_ashrrev_i32_e32 v187, 31, v186
	v_cndmask_b32_e32 v128, v219, v128, vcc
	v_lshl_add_u64 v[188:189], v[180:181], 0, s[34:35]
	v_lshlrev_b64 v[210:211], 11, v[186:187]
	v_lshlrev_b32_e32 v204, 2, v128
	v_lshl_add_u64 v[128:129], v[188:189], 0, v[210:211]
	global_load_dwordx4 v[206:209], v[128:129], off
	global_load_dwordx4 v[152:155], v[128:129], off offset:256
	v_or_b32_e32 v198, 16, v186
	v_ashrrev_i32_e32 v199, 31, v198
	v_or_b32_e32 v192, 32, v186
	v_lshlrev_b64 v[200:201], 11, v[198:199]
	v_ashrrev_i32_e32 v193, 31, v192
	v_or_b32_e32 v190, 48, v186
	v_lshl_add_u64 v[128:129], v[188:189], 0, v[200:201]
	v_lshlrev_b64 v[196:197], 11, v[192:193]
	v_ashrrev_i32_e32 v191, 31, v190
	global_load_dwordx4 v[148:151], v[128:129], off
	global_load_dwordx4 v[144:147], v[128:129], off offset:256
	v_lshl_add_u64 v[128:129], v[188:189], 0, v[196:197]
	v_lshlrev_b64 v[194:195], 11, v[190:191]
	global_load_dwordx4 v[140:143], v[128:129], off
	global_load_dwordx4 v[136:139], v[128:129], off offset:256
	v_lshl_add_u64 v[128:129], v[188:189], 0, v[194:195]
	global_load_dwordx4 v[132:135], v[128:129], off
	s_nop 0
	global_load_dwordx4 v[128:131], v[128:129], off offset:256
	v_lshl_add_u64 v[210:211], s[94:95], 0, v[210:211]
	s_lshl_b32 s42, s20, 2
	v_lshl_add_u64 v[210:211], v[210:211], 0, s[34:35]
	s_lshl_b32 s20, s6, 1
	v_lshl_add_u64 v[210:211], v[210:211], 0, s[20:21]
	v_lshlrev_b32_e32 v160, 1, v178
	v_lshl_add_u64 v[210:211], v[210:211], 0, v[160:161]
	s_ashr_i32 s43, s42, 31
	s_waitcnt vmcnt(0)
	v_lshlrev_b32_e32 v212, 16, v206
	v_and_b32_e32 v213, 0xffff0000, v206
	v_lshlrev_b32_e32 v206, 16, v207
	v_and_b32_e32 v207, 0xffff0000, v207
	v_lshlrev_b32_e32 v222, 16, v208
	v_and_b32_e32 v223, 0xffff0000, v208
	v_lshlrev_b32_e32 v208, 16, v209
	v_and_b32_e32 v209, 0xffff0000, v209
	v_pk_fma_f32 v[126:127], v[126:127], 0.5, v[206:207] op_sel_hi:[1,0,1]
	v_pk_fma_f32 v[124:125], v[124:125], 0.5, v[212:213] op_sel_hi:[1,0,1]
	v_pk_fma_f32 v[206:207], v[122:123], 0.5, v[208:209] op_sel_hi:[1,0,1]
	v_pk_fma_f32 v[208:209], v[120:121], 0.5, v[222:223] op_sel_hi:[1,0,1]
	v_cvt_pk_bf16_f32 v120, v124, v125
	v_cvt_pk_bf16_f32 v121, v126, v127
	v_cvt_pk_bf16_f32 v122, v208, v209
	v_cvt_pk_bf16_f32 v123, v206, v207
	global_store_dwordx4 v[210:211], v[120:123], off
	s_nop 1
	v_mul_f32_e32 v120, v208, v208
	v_mul_f32_e32 v121, v209, v209
	v_fmac_f32_e32 v120, v124, v124
	v_fmac_f32_e32 v121, v125, v125
	v_add_f32_e32 v120, v120, v121
	v_mul_f32_e32 v121, v206, v206
	v_fmac_f32_e32 v121, v126, v126
	v_add_f32_e32 v120, v121, v120
	v_mul_f32_e32 v121, v207, v207
	v_fmac_f32_e32 v121, v127, v127
	v_add_f32_e32 v206, v121, v120
	v_lshlrev_b32_e32 v120, 16, v152
	v_and_b32_e32 v121, 0xffff0000, v152
	v_lshlrev_b32_e32 v122, 16, v153
	v_and_b32_e32 v123, 0xffff0000, v153
	v_lshlrev_b32_e32 v124, 16, v154
	v_and_b32_e32 v125, 0xffff0000, v154
	v_lshlrev_b32_e32 v126, 16, v155
	v_and_b32_e32 v127, 0xffff0000, v155
	v_pk_fma_f32 v[118:119], v[118:119], 0.5, v[122:123] op_sel_hi:[1,0,1]
	v_pk_fma_f32 v[116:117], v[116:117], 0.5, v[120:121] op_sel_hi:[1,0,1]
	v_pk_fma_f32 v[120:121], v[114:115], 0.5, v[126:127] op_sel_hi:[1,0,1]
	v_pk_fma_f32 v[122:123], v[112:113], 0.5, v[124:125] op_sel_hi:[1,0,1]
	v_cvt_pk_bf16_f32 v112, v116, v117
	v_cvt_pk_bf16_f32 v113, v118, v119
	v_cvt_pk_bf16_f32 v114, v122, v123
	v_cvt_pk_bf16_f32 v115, v120, v121
	global_store_dwordx4 v[210:211], v[112:115], off offset:256
	s_nop 1
	v_mul_f32_e32 v112, v122, v122
	v_fmac_f32_e32 v112, v116, v116
	v_mul_f32_e32 v113, v123, v123
	v_add_f32_e32 v112, v112, v206
	v_fmac_f32_e32 v113, v117, v117
	v_add_f32_e32 v112, v113, v112
	v_mul_f32_e32 v113, v120, v120
	v_fmac_f32_e32 v113, v118, v118
	v_add_f32_e32 v112, v113, v112
	v_mul_f32_e32 v113, v121, v121
	v_fmac_f32_e32 v113, v119, v119
	v_add_f32_e32 v112, v113, v112
	v_mov_b32_e32 v113, v112
	s_nop 1
	v_permlane16_swap_b32_e32 v112, v113
	s_waitcnt lgkmcnt(0)
	v_add_f32_e32 v112, v112, v113
	v_mov_b32_e32 v113, v112
	s_nop 1
	v_permlane32_swap_b32_e32 v112, v113
	s_and_saveexec_b64 s[34:35], s[38:39]
	s_cbranch_execz .LBB0_284
	v_lshlrev_b64 v[114:115], 6, v[186:187]
	v_lshl_add_u64 v[114:115], s[92:93], 0, v[114:115]
	v_lshl_add_u64 v[114:115], s[42:43], 2, v[114:115]
	s_lshl_b32 s48, s71, 2
	s_mov_b32 s49, s21
	v_lshl_add_u64 v[114:115], v[114:115], 0, s[48:49]
	s_waitcnt lgkmcnt(0)
	v_add_f32_e32 v112, v112, v113
	global_store_dword v[114:115], v112, off
; __device__ __forceinline__ float bf_lo(unsigned u) { return __uint_as_float(u << 16); }
; __device__ __forceinline__ float bf_hi(unsigned u) { return __uint_as_float(u & 0xffff0000u); }
; __device__ __forceinline__ u32x4 pack8(f32x4 a, f32x4 b) { u32x4 o; o[0] = cvt_pk_bf16(a[0], a[1]); o[1] = cvt_pk_bf16(a[2], a[3]); o[2] = cvt_pk_bf16(b[0], b[1]); o[3] = cvt_pk_bf16(b[2], b[3]); return o; }
;   __device__ __forceinline__ void operator()(const AccT& acc, const Unit& u, int ui, int wr, int wc, int fr, int fq) const {
;     ...
;       for (int m = 0; m < 4; ++m) {
;         const int row = u.pm * 256 + ai * 128 + wr * 64 + m * 16 + fr; float ss = 0.f;
; #pragma unroll
;         for (int bj = 0; bj < 2; ++bj) {
;           const size_t o = (size_t)row * DM + u.pn * 256 + bj * 128 + wc * 32 + fq * 8;
;           const u32x4 h4 = xh[m][bj];
;           f32x4 y0 = {bf_lo(h4[0]), bf_hi(h4[0]), bf_lo(h4[1]), bf_hi(h4[1])}, y1 = {bf_lo(h4[2]), bf_hi(h4[2]), bf_lo(h4[3]), bf_hi(h4[3])};
;           y0 += acc[ai][bj][m][0] * s; y1 += acc[ai][bj][m][1] * s;
;           *(u32x4*)(XB + o) = pack8(y0, y1);
; #pragma unroll
;           for (int i = 0; i < 4; ++i) ss += y0[i] * y0[i] + y1[i] * y1[i];
;         }
;         ss += __shfl_xor(ss, 16); ss += __shfl_xor(ss, 32);
;         if (fq == 0) RSS[(size_t)row * 16 + u.pn * 4 + wc] = ss;
.LBB0_284:
	s_or_b64 exec, exec, s[34:35]
	v_lshlrev_b32_e32 v114, 16, v149
	v_and_b32_e32 v115, 0xffff0000, v149
	v_lshlrev_b32_e32 v116, 16, v150
	v_and_b32_e32 v117, 0xffff0000, v150
	v_lshlrev_b32_e32 v112, 16, v148
	s_waitcnt lgkmcnt(0)
	v_and_b32_e32 v113, 0xffff0000, v148
	v_lshlrev_b32_e32 v118, 16, v151
	v_and_b32_e32 v119, 0xffff0000, v151
	v_pk_fma_f32 v[110:111], v[110:111], 0.5, v[114:115] op_sel_hi:[1,0,1]
	v_pk_fma_f32 v[114:115], v[104:105], 0.5, v[116:117] op_sel_hi:[1,0,1]
	v_pk_fma_f32 v[108:109], v[108:109], 0.5, v[112:113] op_sel_hi:[1,0,1]
	v_pk_fma_f32 v[112:113], v[106:107], 0.5, v[118:119] op_sel_hi:[1,0,1]
	v_cvt_pk_bf16_f32 v106, v114, v115
	v_mul_f32_e32 v114, v114, v114
	v_cvt_pk_bf16_f32 v104, v108, v109
	v_fmac_f32_e32 v114, v108, v108
	v_mul_f32_e32 v108, v115, v115
	v_fmac_f32_e32 v108, v109, v109
	v_mul_f32_e32 v109, v112, v112
	v_add_f32_e32 v108, v114, v108
	v_fmac_f32_e32 v109, v110, v110
	v_add_f32_e32 v108, v109, v108
	v_mul_f32_e32 v109, v113, v113
	v_cvt_pk_bf16_f32 v105, v110, v111
	v_cvt_pk_bf16_f32 v107, v112, v113
	v_fmac_f32_e32 v109, v111, v111
	v_lshlrev_b32_e32 v110, 16, v145
	v_and_b32_e32 v111, 0xffff0000, v145
	v_lshlrev_b32_e32 v112, 16, v146
	v_and_b32_e32 v113, 0xffff0000, v146
	v_add_f32_e32 v118, v109, v108
	v_lshlrev_b32_e32 v108, 16, v144
	v_and_b32_e32 v109, 0xffff0000, v144
	v_pk_fma_f32 v[102:103], v[102:103], 0.5, v[110:111] op_sel_hi:[1,0,1]
	v_pk_fma_f32 v[110:111], v[96:97], 0.5, v[112:113] op_sel_hi:[1,0,1]
	v_pk_fma_f32 v[100:101], v[100:101], 0.5, v[108:109] op_sel_hi:[1,0,1]
	v_mul_f32_e32 v96, v110, v110
	v_lshlrev_b32_e32 v114, 16, v147
	v_and_b32_e32 v115, 0xffff0000, v147
	v_fmac_f32_e32 v96, v100, v100
	v_mul_f32_e32 v97, v111, v111
	v_pk_fma_f32 v[108:109], v[98:99], 0.5, v[114:115] op_sel_hi:[1,0,1]
	v_add_f32_e32 v96, v96, v118
	v_fmac_f32_e32 v97, v101, v101
	v_add_f32_e32 v96, v97, v96
	v_mul_f32_e32 v97, v108, v108
	v_fmac_f32_e32 v97, v102, v102
	v_add_f32_e32 v96, v97, v96
	v_mul_f32_e32 v97, v109, v109
	v_fmac_f32_e32 v97, v103, v103
	v_add_f32_e32 v99, v97, v96
	v_mov_b32_e32 v114, v99
	s_nop 1
	v_permlane16_swap_b32_e32 v99, v114
	v_lshl_add_u64 v[116:117], s[94:95], 0, v[200:201]
	v_lshl_add_u64 v[116:117], s[44:45], 1, v[116:117]
	v_lshl_add_u64 v[96:97], v[116:117], 0, s[20:21]
	v_lshl_add_u64 v[112:113], v[96:97], 0, v[160:161]
	s_waitcnt lgkmcnt(0)
	v_add_f32_e32 v96, v99, v114
	v_mov_b32_e32 v97, v96
	s_nop 1
	v_permlane32_swap_b32_e32 v96, v97
	v_cvt_pk_bf16_f32 v98, v100, v101
	v_cvt_pk_bf16_f32 v99, v102, v103
	v_cvt_pk_bf16_f32 v100, v110, v111
	v_cvt_pk_bf16_f32 v101, v108, v109
	global_store_dwordx4 v[112:113], v[104:107], off
	global_store_dwordx4 v[112:113], v[98:101], off offset:256
	s_and_saveexec_b64 s[34:35], s[38:39]
	s_cbranch_execz .LBB0_286
	v_lshlrev_b64 v[98:99], 6, v[198:199]
	v_lshl_add_u64 v[98:99], s[92:93], 0, v[98:99]
	v_lshl_add_u64 v[98:99], s[42:43], 2, v[98:99]
	s_lshl_b32 s48, s71, 2
	s_mov_b32 s49, s21
	v_lshl_add_u64 v[98:99], v[98:99], 0, s[48:49]
	s_waitcnt lgkmcnt(0)
	v_add_f32_e32 v96, v96, v97
	global_store_dword v[98:99], v96, off
.LBB0_286:
	s_or_b64 exec, exec, s[34:35]
	v_lshlrev_b32_e32 v98, 16, v141
	v_and_b32_e32 v99, 0xffff0000, v141
	v_lshlrev_b32_e32 v100, 16, v142
	v_and_b32_e32 v101, 0xffff0000, v142
	v_lshlrev_b32_e32 v96, 16, v140
	s_waitcnt lgkmcnt(0)
	v_and_b32_e32 v97, 0xffff0000, v140
	v_lshlrev_b32_e32 v102, 16, v143
	v_and_b32_e32 v103, 0xffff0000, v143
	v_pk_fma_f32 v[94:95], v[94:95], 0.5, v[98:99] op_sel_hi:[1,0,1]
	v_pk_fma_f32 v[98:99], v[88:89], 0.5, v[100:101] op_sel_hi:[1,0,1]
	v_pk_fma_f32 v[92:93], v[92:93], 0.5, v[96:97] op_sel_hi:[1,0,1]
	v_pk_fma_f32 v[96:97], v[90:91], 0.5, v[102:103] op_sel_hi:[1,0,1]
	v_cvt_pk_bf16_f32 v90, v98, v99
	v_mul_f32_e32 v98, v98, v98
	v_cvt_pk_bf16_f32 v88, v92, v93
	v_fmac_f32_e32 v98, v92, v92
	v_mul_f32_e32 v92, v99, v99
	v_fmac_f32_e32 v92, v93, v93
	v_mul_f32_e32 v93, v96, v96
	v_add_f32_e32 v92, v98, v92
	v_fmac_f32_e32 v93, v94, v94
	v_add_f32_e32 v92, v93, v92
	v_mul_f32_e32 v93, v97, v97
	v_cvt_pk_bf16_f32 v89, v94, v95
	v_cvt_pk_bf16_f32 v91, v96, v97
	v_fmac_f32_e32 v93, v95, v95
	v_lshlrev_b32_e32 v94, 16, v137
	v_and_b32_e32 v95, 0xffff0000, v137
	v_lshlrev_b32_e32 v96, 16, v138
	v_and_b32_e32 v97, 0xffff0000, v138
	v_add_f32_e32 v102, v93, v92
	v_lshlrev_b32_e32 v92, 16, v136
	v_and_b32_e32 v93, 0xffff0000, v136
	v_pk_fma_f32 v[86:87], v[86:87], 0.5, v[94:95] op_sel_hi:[1,0,1]
	v_pk_fma_f32 v[94:95], v[80:81], 0.5, v[96:97] op_sel_hi:[1,0,1]
	v_pk_fma_f32 v[84:85], v[84:85], 0.5, v[92:93] op_sel_hi:[1,0,1]
	v_mul_f32_e32 v80, v94, v94
	v_lshlrev_b32_e32 v98, 16, v139
	v_and_b32_e32 v99, 0xffff0000, v139
	v_fmac_f32_e32 v80, v84, v84
	v_mul_f32_e32 v81, v95, v95
	v_pk_fma_f32 v[92:93], v[82:83], 0.5, v[98:99] op_sel_hi:[1,0,1]
	v_add_f32_e32 v80, v80, v102
	v_fmac_f32_e32 v81, v85, v85
	v_add_f32_e32 v80, v81, v80
	v_mul_f32_e32 v81, v92, v92
	v_fmac_f32_e32 v81, v86, v86
	v_add_f32_e32 v80, v81, v80
	v_mul_f32_e32 v81, v93, v93
	v_fmac_f32_e32 v81, v87, v87
	v_add_f32_e32 v83, v81, v80
	v_mov_b32_e32 v98, v83
	s_nop 1
	v_permlane16_swap_b32_e32 v83, v98
	v_lshl_add_u64 v[100:101], s[94:95], 0, v[196:197]
	v_lshl_add_u64 v[100:101], s[44:45], 1, v[100:101]
	v_lshl_add_u64 v[80:81], v[100:101], 0, s[20:21]
	v_lshl_add_u64 v[96:97], v[80:81], 0, v[160:161]
	s_waitcnt lgkmcnt(0)
	v_add_f32_e32 v80, v83, v98
	v_mov_b32_e32 v81, v80
	s_nop 1
	v_permlane32_swap_b32_e32 v80, v81
	v_cvt_pk_bf16_f32 v82, v84, v85
	v_cvt_pk_bf16_f32 v83, v86, v87
	v_cvt_pk_bf16_f32 v84, v94, v95
	v_cvt_pk_bf16_f32 v85, v92, v93
	global_store_dwordx4 v[96:97], v[88:91], off
	global_store_dwordx4 v[96:97], v[82:85], off offset:256
	s_and_saveexec_b64 s[34:35], s[38:39]
	s_cbranch_execz .LBB0_288
	v_lshlrev_b64 v[82:83], 6, v[192:193]
	v_lshl_add_u64 v[82:83], s[92:93], 0, v[82:83]
	v_lshl_add_u64 v[82:83], s[42:43], 2, v[82:83]
	s_lshl_b32 s48, s71, 2
	s_mov_b32 s49, s21
	v_lshl_add_u64 v[82:83], v[82:83], 0, s[48:49]
	s_waitcnt lgkmcnt(0)
	v_add_f32_e32 v80, v80, v81
	global_store_dword v[82:83], v80, off
; __device__ __forceinline__ float bf_lo(unsigned u) { return __uint_as_float(u << 16); }
; __device__ __forceinline__ float bf_hi(unsigned u) { return __uint_as_float(u & 0xffff0000u); }
; __device__ __forceinline__ u32x4 pack8(f32x4 a, f32x4 b) { u32x4 o; o[0] = cvt_pk_bf16(a[0], a[1]); o[1] = cvt_pk_bf16(a[2], a[3]); o[2] = cvt_pk_bf16(b[0], b[1]); o[3] = cvt_pk_bf16(b[2], b[3]); return o; }
;   __device__ __forceinline__ void operator()(const AccT& acc, const Unit& u, int ui, int wr, int wc, int fr, int fq) const {
;     ...
;           xh[m][bj] = *(const u32x4*)(XB + (size_t)(u.pm * 256 + ai * 128 + wr * 64 + m * 16 + fr) * DM + u.pn * 256 + bj * 128 + wc * 32 + fq * 8);
; #pragma unroll
;       for (int m = 0; m < 4; ++m) {
;         const int row = u.pm * 256 + ai * 128 + wr * 64 + m * 16 + fr; float ss = 0.f;
; #pragma unroll
;         for (int bj = 0; bj < 2; ++bj) {
;           const size_t o = (size_t)row * DM + u.pn * 256 + bj * 128 + wc * 32 + fq * 8;
;           const u32x4 h4 = xh[m][bj];
;           f32x4 y0 = {bf_lo(h4[0]), bf_hi(h4[0]), bf_lo(h4[1]), bf_hi(h4[1])}, y1 = {bf_lo(h4[2]), bf_hi(h4[2]), bf_lo(h4[3]), bf_hi(h4[3])};
;           y0 += acc[ai][bj][m][0] * s; y1 += acc[ai][bj][m][1] * s;
;           *(u32x4*)(XB + o) = pack8(y0, y1);
; #pragma unroll
;           for (int i = 0; i < 4; ++i) ss += y0[i] * y0[i] + y1[i] * y1[i];
;         }
;         ss += __shfl_xor(ss, 16); ss += __shfl_xor(ss, 32);
;         if (fq == 0) RSS[(size_t)row * 16 + u.pn * 4 + wc] = ss;
.LBB0_288:
	s_or_b64 exec, exec, s[34:35]
	v_lshlrev_b32_e32 v82, 16, v133
	v_and_b32_e32 v83, 0xffff0000, v133
	v_lshlrev_b32_e32 v84, 16, v134
	v_and_b32_e32 v85, 0xffff0000, v134
	v_lshlrev_b32_e32 v80, 16, v132
	s_waitcnt lgkmcnt(0)
	v_and_b32_e32 v81, 0xffff0000, v132
	v_lshlrev_b32_e32 v86, 16, v135
	v_and_b32_e32 v87, 0xffff0000, v135
	v_pk_fma_f32 v[78:79], v[78:79], 0.5, v[82:83] op_sel_hi:[1,0,1]
	v_pk_fma_f32 v[82:83], v[72:73], 0.5, v[84:85] op_sel_hi:[1,0,1]
	v_pk_fma_f32 v[76:77], v[76:77], 0.5, v[80:81] op_sel_hi:[1,0,1]
	v_pk_fma_f32 v[80:81], v[74:75], 0.5, v[86:87] op_sel_hi:[1,0,1]
	v_cvt_pk_bf16_f32 v74, v82, v83
	v_mul_f32_e32 v82, v82, v82
	v_cvt_pk_bf16_f32 v72, v76, v77
	v_fmac_f32_e32 v82, v76, v76
	v_mul_f32_e32 v76, v83, v83
	v_fmac_f32_e32 v76, v77, v77
	v_mul_f32_e32 v77, v80, v80
	v_add_f32_e32 v76, v82, v76
	v_fmac_f32_e32 v77, v78, v78
	v_add_f32_e32 v76, v77, v76
	v_mul_f32_e32 v77, v81, v81
	v_cvt_pk_bf16_f32 v73, v78, v79
	v_cvt_pk_bf16_f32 v75, v80, v81
	v_fmac_f32_e32 v77, v79, v79
	v_lshlrev_b32_e32 v78, 16, v129
	v_and_b32_e32 v79, 0xffff0000, v129
	v_lshlrev_b32_e32 v80, 16, v130
	v_and_b32_e32 v81, 0xffff0000, v130
	v_add_f32_e32 v86, v77, v76
	v_lshlrev_b32_e32 v76, 16, v128
	v_and_b32_e32 v77, 0xffff0000, v128
	v_pk_fma_f32 v[70:71], v[70:71], 0.5, v[78:79] op_sel_hi:[1,0,1]
	v_pk_fma_f32 v[78:79], v[64:65], 0.5, v[80:81] op_sel_hi:[1,0,1]
	v_pk_fma_f32 v[68:69], v[68:69], 0.5, v[76:77] op_sel_hi:[1,0,1]
	v_mul_f32_e32 v64, v78, v78
	v_lshlrev_b32_e32 v82, 16, v131
	v_and_b32_e32 v83, 0xffff0000, v131
	v_fmac_f32_e32 v64, v68, v68
	v_mul_f32_e32 v65, v79, v79
	v_pk_fma_f32 v[76:77], v[66:67], 0.5, v[82:83] op_sel_hi:[1,0,1]
	v_add_f32_e32 v64, v64, v86
	v_fmac_f32_e32 v65, v69, v69
	v_add_f32_e32 v64, v65, v64
	v_mul_f32_e32 v65, v76, v76
	v_fmac_f32_e32 v65, v70, v70
	v_add_f32_e32 v64, v65, v64
	v_mul_f32_e32 v65, v77, v77
	v_fmac_f32_e32 v65, v71, v71
	v_add_f32_e32 v67, v65, v64
	v_mov_b32_e32 v82, v67
	s_nop 1
	v_permlane16_swap_b32_e32 v67, v82
	v_lshl_add_u64 v[84:85], s[94:95], 0, v[194:195]
	v_lshl_add_u64 v[84:85], s[44:45], 1, v[84:85]
	v_lshl_add_u64 v[64:65], v[84:85], 0, s[20:21]
	v_lshl_add_u64 v[80:81], v[64:65], 0, v[160:161]
	s_waitcnt lgkmcnt(0)
	v_add_f32_e32 v64, v67, v82
	v_mov_b32_e32 v65, v64
	s_nop 1
	v_permlane32_swap_b32_e32 v64, v65
	v_cvt_pk_bf16_f32 v66, v68, v69
	v_cvt_pk_bf16_f32 v67, v70, v71
	v_cvt_pk_bf16_f32 v68, v78, v79
	v_cvt_pk_bf16_f32 v69, v76, v77
	global_store_dwordx4 v[80:81], v[72:75], off
	global_store_dwordx4 v[80:81], v[66:69], off offset:256
	s_and_saveexec_b64 s[34:35], s[38:39]
	s_cbranch_execz .LBB0_290
	v_lshlrev_b64 v[66:67], 6, v[190:191]
	v_lshl_add_u64 v[66:67], s[92:93], 0, v[66:67]
	v_lshl_add_u64 v[66:67], s[42:43], 2, v[66:67]
	s_lshl_b32 s48, s71, 2
	s_mov_b32 s49, s21
	v_lshl_add_u64 v[66:67], v[66:67], 0, s[48:49]
	s_waitcnt lgkmcnt(0)
	v_add_f32_e32 v64, v64, v65
	global_store_dword v[66:67], v64, off
.LBB0_290:
	s_or_b64 exec, exec, s[34:35]
	v_add_u32_e32 v104, 0x80, v186
	v_ashrrev_i32_e32 v105, 31, v104
	v_lshlrev_b64 v[110:111], 11, v[104:105]
	s_waitcnt lgkmcnt(0)
	v_lshl_add_u64 v[64:65], v[188:189], 0, v[110:111]
	global_load_dwordx4 v[106:109], v[64:65], off
	global_load_dwordx4 v[88:91], v[64:65], off offset:256
	v_add_u32_e32 v100, 0x90, v186
	v_ashrrev_i32_e32 v101, 31, v100
	v_add_u32_e32 v94, 0xa0, v186
	v_lshlrev_b64 v[102:103], 11, v[100:101]
	v_ashrrev_i32_e32 v95, 31, v94
	v_add_u32_e32 v92, 0xb0, v186
	v_lshl_add_u64 v[64:65], v[188:189], 0, v[102:103]
	v_lshlrev_b64 v[98:99], 11, v[94:95]
	v_ashrrev_i32_e32 v93, 31, v92
	global_load_dwordx4 v[84:87], v[64:65], off
	global_load_dwordx4 v[80:83], v[64:65], off offset:256
	v_lshl_add_u64 v[64:65], v[188:189], 0, v[98:99]
	v_lshlrev_b64 v[96:97], 11, v[92:93]
	global_load_dwordx4 v[76:79], v[64:65], off
	global_load_dwordx4 v[72:75], v[64:65], off offset:256
	v_lshl_add_u64 v[64:65], v[188:189], 0, v[96:97]
	global_load_dwordx4 v[68:71], v[64:65], off
	s_nop 0
	global_load_dwordx4 v[64:67], v[64:65], off offset:256
	v_lshl_add_u64 v[110:111], s[94:95], 0, v[110:111]
	v_lshl_add_u64 v[110:111], s[44:45], 1, v[110:111]
	v_lshl_add_u64 v[110:111], v[110:111], 0, s[20:21]
	v_lshl_add_u64 v[110:111], v[110:111], 0, v[160:161]
	s_waitcnt vmcnt(7)
	v_lshlrev_b32_e32 v112, 16, v106
	v_and_b32_e32 v113, 0xffff0000, v106
	v_lshlrev_b32_e32 v106, 16, v107
	v_and_b32_e32 v107, 0xffff0000, v107
	v_lshlrev_b32_e32 v114, 16, v108
	v_and_b32_e32 v115, 0xffff0000, v108
	v_lshlrev_b32_e32 v108, 16, v109
	v_and_b32_e32 v109, 0xffff0000, v109
	v_pk_fma_f32 v[62:63], v[62:63], 0.5, v[106:107] op_sel_hi:[1,0,1]
	v_pk_fma_f32 v[60:61], v[60:61], 0.5, v[112:113] op_sel_hi:[1,0,1]
	v_pk_fma_f32 v[106:107], v[58:59], 0.5, v[108:109] op_sel_hi:[1,0,1]
	v_pk_fma_f32 v[108:109], v[56:57], 0.5, v[114:115] op_sel_hi:[1,0,1]
	v_cvt_pk_bf16_f32 v56, v60, v61
	v_cvt_pk_bf16_f32 v57, v62, v63
	v_cvt_pk_bf16_f32 v58, v108, v109
	v_cvt_pk_bf16_f32 v59, v106, v107
	global_store_dwordx4 v[110:111], v[56:59], off
	s_nop 1
	v_mul_f32_e32 v56, v108, v108
	v_mul_f32_e32 v57, v109, v109
	v_fmac_f32_e32 v56, v60, v60
	v_fmac_f32_e32 v57, v61, v61
	v_add_f32_e32 v56, v56, v57
	v_mul_f32_e32 v57, v106, v106
	v_fmac_f32_e32 v57, v62, v62
	v_add_f32_e32 v56, v57, v56
	v_mul_f32_e32 v57, v107, v107
	v_fmac_f32_e32 v57, v63, v63
	v_add_f32_e32 v106, v57, v56
	s_waitcnt vmcnt(7)
	v_lshlrev_b32_e32 v56, 16, v88
	v_and_b32_e32 v57, 0xffff0000, v88
	v_lshlrev_b32_e32 v58, 16, v89
	v_and_b32_e32 v59, 0xffff0000, v89
	v_lshlrev_b32_e32 v60, 16, v90
	v_and_b32_e32 v61, 0xffff0000, v90
	v_lshlrev_b32_e32 v62, 16, v91
	v_and_b32_e32 v63, 0xffff0000, v91
	v_pk_fma_f32 v[54:55], v[54:55], 0.5, v[58:59] op_sel_hi:[1,0,1]
	v_pk_fma_f32 v[52:53], v[52:53], 0.5, v[56:57] op_sel_hi:[1,0,1]
	v_pk_fma_f32 v[56:57], v[50:51], 0.5, v[62:63] op_sel_hi:[1,0,1]
	v_pk_fma_f32 v[58:59], v[48:49], 0.5, v[60:61] op_sel_hi:[1,0,1]
	v_cvt_pk_bf16_f32 v48, v52, v53
	v_cvt_pk_bf16_f32 v49, v54, v55
	v_cvt_pk_bf16_f32 v50, v58, v59
	v_cvt_pk_bf16_f32 v51, v56, v57
	global_store_dwordx4 v[110:111], v[48:51], off offset:256
	s_nop 1
	v_mul_f32_e32 v48, v58, v58
	v_fmac_f32_e32 v48, v52, v52
	v_mul_f32_e32 v49, v59, v59
	v_add_f32_e32 v48, v48, v106
	v_fmac_f32_e32 v49, v53, v53
	v_add_f32_e32 v48, v49, v48
	v_mul_f32_e32 v49, v56, v56
	v_fmac_f32_e32 v49, v54, v54
	v_add_f32_e32 v48, v49, v48
	v_mul_f32_e32 v49, v57, v57
	v_fmac_f32_e32 v49, v55, v55
	v_add_f32_e32 v48, v49, v48
	v_mov_b32_e32 v49, v48
	s_nop 1
	v_permlane16_swap_b32_e32 v48, v49
	s_waitcnt lgkmcnt(0)
	v_add_f32_e32 v48, v48, v49
	v_mov_b32_e32 v49, v48
	s_nop 1
	v_permlane32_swap_b32_e32 v48, v49
	s_and_saveexec_b64 s[34:35], s[38:39]
	s_cbranch_execz .LBB0_292
; __device__ __forceinline__ float bf_lo(unsigned u) { return __uint_as_float(u << 16); }
; __device__ __forceinline__ float bf_hi(unsigned u) { return __uint_as_float(u & 0xffff0000u); }
; __device__ __forceinline__ u32x4 pack8(f32x4 a, f32x4 b) { u32x4 o; o[0] = cvt_pk_bf16(a[0], a[1]); o[1] = cvt_pk_bf16(a[2], a[3]); o[2] = cvt_pk_bf16(b[0], b[1]); o[3] = cvt_pk_bf16(b[2], b[3]); return o; }
;   __device__ __forceinline__ void operator()(const AccT& acc, const Unit& u, int ui, int wr, int wc, int fr, int fq) const {
;     ...
;       for (int m = 0; m < 4; ++m) {
;         const int row = u.pm * 256 + ai * 128 + wr * 64 + m * 16 + fr; float ss = 0.f;
; #pragma unroll
;         for (int bj = 0; bj < 2; ++bj) {
;           const size_t o = (size_t)row * DM + u.pn * 256 + bj * 128 + wc * 32 + fq * 8;
;           const u32x4 h4 = xh[m][bj];
;           f32x4 y0 = {bf_lo(h4[0]), bf_hi(h4[0]), bf_lo(h4[1]), bf_hi(h4[1])}, y1 = {bf_lo(h4[2]), bf_hi(h4[2]), bf_lo(h4[3]), bf_hi(h4[3])};
;           y0 += acc[ai][bj][m][0] * s; y1 += acc[ai][bj][m][1] * s;
;           *(u32x4*)(XB + o) = pack8(y0, y1);
; #pragma unroll
;           for (int i = 0; i < 4; ++i) ss += y0[i] * y0[i] + y1[i] * y1[i];
;         }
;         ss += __shfl_xor(ss, 16); ss += __shfl_xor(ss, 32);
;         if (fq == 0) RSS[(size_t)row * 16 + u.pn * 4 + wc] = ss;
	v_lshlrev_b64 v[50:51], 6, v[104:105]
	v_lshl_add_u64 v[50:51], s[92:93], 0, v[50:51]
	v_lshl_add_u64 v[50:51], s[42:43], 2, v[50:51]
	s_lshl_b32 s48, s71, 2
	s_mov_b32 s49, s21
	v_lshl_add_u64 v[50:51], v[50:51], 0, s[48:49]
	s_waitcnt lgkmcnt(0)
	v_add_f32_e32 v48, v48, v49
	global_store_dword v[50:51], v48, off
.LBB0_292:
	s_or_b64 exec, exec, s[34:35]
	s_waitcnt vmcnt(7)
	v_lshlrev_b32_e32 v50, 16, v85
	v_and_b32_e32 v51, 0xffff0000, v85
	v_lshlrev_b32_e32 v52, 16, v86
	v_and_b32_e32 v53, 0xffff0000, v86
	v_lshlrev_b32_e32 v48, 16, v84
	s_waitcnt lgkmcnt(0)
	v_and_b32_e32 v49, 0xffff0000, v84
	v_lshlrev_b32_e32 v54, 16, v87
	v_and_b32_e32 v55, 0xffff0000, v87
	v_pk_fma_f32 v[46:47], v[46:47], 0.5, v[50:51] op_sel_hi:[1,0,1]
	v_pk_fma_f32 v[50:51], v[40:41], 0.5, v[52:53] op_sel_hi:[1,0,1]
	v_pk_fma_f32 v[44:45], v[44:45], 0.5, v[48:49] op_sel_hi:[1,0,1]
	v_pk_fma_f32 v[48:49], v[42:43], 0.5, v[54:55] op_sel_hi:[1,0,1]
	v_cvt_pk_bf16_f32 v42, v50, v51
	v_mul_f32_e32 v50, v50, v50
	v_cvt_pk_bf16_f32 v40, v44, v45
	v_fmac_f32_e32 v50, v44, v44
	v_mul_f32_e32 v44, v51, v51
	v_fmac_f32_e32 v44, v45, v45
	v_mul_f32_e32 v45, v48, v48
	v_add_f32_e32 v44, v50, v44
	v_fmac_f32_e32 v45, v46, v46
	v_add_f32_e32 v44, v45, v44
	v_mul_f32_e32 v45, v49, v49
	v_cvt_pk_bf16_f32 v41, v46, v47
	v_cvt_pk_bf16_f32 v43, v48, v49
	v_fmac_f32_e32 v45, v47, v47
	s_waitcnt vmcnt(6)
	v_lshlrev_b32_e32 v46, 16, v81
	v_and_b32_e32 v47, 0xffff0000, v81
	v_lshlrev_b32_e32 v48, 16, v82
	v_and_b32_e32 v49, 0xffff0000, v82
	v_add_f32_e32 v54, v45, v44
	v_lshlrev_b32_e32 v44, 16, v80
	v_and_b32_e32 v45, 0xffff0000, v80
	v_pk_fma_f32 v[38:39], v[38:39], 0.5, v[46:47] op_sel_hi:[1,0,1]
	v_pk_fma_f32 v[46:47], v[32:33], 0.5, v[48:49] op_sel_hi:[1,0,1]
	v_pk_fma_f32 v[36:37], v[36:37], 0.5, v[44:45] op_sel_hi:[1,0,1]
	v_mul_f32_e32 v32, v46, v46
	v_lshlrev_b32_e32 v50, 16, v83
	v_and_b32_e32 v51, 0xffff0000, v83
	v_fmac_f32_e32 v32, v36, v36
	v_mul_f32_e32 v33, v47, v47
	v_pk_fma_f32 v[44:45], v[34:35], 0.5, v[50:51] op_sel_hi:[1,0,1]
	v_add_f32_e32 v32, v32, v54
	v_fmac_f32_e32 v33, v37, v37
	v_add_f32_e32 v32, v33, v32
	v_mul_f32_e32 v33, v44, v44
	v_fmac_f32_e32 v33, v38, v38
	v_add_f32_e32 v32, v33, v32
	v_mul_f32_e32 v33, v45, v45
	v_fmac_f32_e32 v33, v39, v39
	v_add_f32_e32 v35, v33, v32
	v_mov_b32_e32 v50, v35
	s_nop 1
	v_permlane16_swap_b32_e32 v35, v50
	v_lshl_add_u64 v[52:53], s[94:95], 0, v[102:103]
	v_lshl_add_u64 v[52:53], s[44:45], 1, v[52:53]
	v_lshl_add_u64 v[32:33], v[52:53], 0, s[20:21]
	v_lshl_add_u64 v[48:49], v[32:33], 0, v[160:161]
	s_waitcnt lgkmcnt(0)
	v_add_f32_e32 v32, v35, v50
	v_mov_b32_e32 v33, v32
	s_nop 1
	v_permlane32_swap_b32_e32 v32, v33
	v_cvt_pk_bf16_f32 v34, v36, v37
	v_cvt_pk_bf16_f32 v35, v38, v39
	v_cvt_pk_bf16_f32 v36, v46, v47
	v_cvt_pk_bf16_f32 v37, v44, v45
	global_store_dwordx4 v[48:49], v[40:43], off
	global_store_dwordx4 v[48:49], v[34:37], off offset:256
	s_and_saveexec_b64 s[34:35], s[38:39]
	s_cbranch_execz .LBB0_294
	v_lshlrev_b64 v[34:35], 6, v[100:101]
	v_lshl_add_u64 v[34:35], s[92:93], 0, v[34:35]
	v_lshl_add_u64 v[34:35], s[42:43], 2, v[34:35]
	s_lshl_b32 s48, s71, 2
	s_mov_b32 s49, s21
	v_lshl_add_u64 v[34:35], v[34:35], 0, s[48:49]
	s_waitcnt lgkmcnt(0)
	v_add_f32_e32 v32, v32, v33
	global_store_dword v[34:35], v32, off
; __device__ __forceinline__ float bf_lo(unsigned u) { return __uint_as_float(u << 16); }
; __device__ __forceinline__ float bf_hi(unsigned u) { return __uint_as_float(u & 0xffff0000u); }
; __device__ __forceinline__ u32x4 pack8(f32x4 a, f32x4 b) { u32x4 o; o[0] = cvt_pk_bf16(a[0], a[1]); o[1] = cvt_pk_bf16(a[2], a[3]); o[2] = cvt_pk_bf16(b[0], b[1]); o[3] = cvt_pk_bf16(b[2], b[3]); return o; }
;   __device__ __forceinline__ void operator()(const AccT& acc, const Unit& u, int ui, int wr, int wc, int fr, int fq) const {
;     ...
;       for (int m = 0; m < 4; ++m) {
;         const int row = u.pm * 256 + ai * 128 + wr * 64 + m * 16 + fr; float ss = 0.f;
; #pragma unroll
;         for (int bj = 0; bj < 2; ++bj) {
;           const size_t o = (size_t)row * DM + u.pn * 256 + bj * 128 + wc * 32 + fq * 8;
;           const u32x4 h4 = xh[m][bj];
;           f32x4 y0 = {bf_lo(h4[0]), bf_hi(h4[0]), bf_lo(h4[1]), bf_hi(h4[1])}, y1 = {bf_lo(h4[2]), bf_hi(h4[2]), bf_lo(h4[3]), bf_hi(h4[3])};
;           y0 += acc[ai][bj][m][0] * s; y1 += acc[ai][bj][m][1] * s;
;           *(u32x4*)(XB + o) = pack8(y0, y1);
; #pragma unroll
;           for (int i = 0; i < 4; ++i) ss += y0[i] * y0[i] + y1[i] * y1[i];
;         }
;         ss += __shfl_xor(ss, 16); ss += __shfl_xor(ss, 32);
;         if (fq == 0) RSS[(size_t)row * 16 + u.pn * 4 + wc] = ss;
;       }
.LBB0_294:
	s_or_b64 exec, exec, s[34:35]
	s_waitcnt vmcnt(7)
	v_lshlrev_b32_e32 v34, 16, v77
	v_and_b32_e32 v35, 0xffff0000, v77
	v_lshlrev_b32_e32 v36, 16, v78
	v_and_b32_e32 v37, 0xffff0000, v78
	v_lshlrev_b32_e32 v32, 16, v76
	s_waitcnt lgkmcnt(0)
	v_and_b32_e32 v33, 0xffff0000, v76
	v_lshlrev_b32_e32 v38, 16, v79
	v_and_b32_e32 v39, 0xffff0000, v79
	v_pk_fma_f32 v[30:31], v[30:31], 0.5, v[34:35] op_sel_hi:[1,0,1]
	v_pk_fma_f32 v[34:35], v[24:25], 0.5, v[36:37] op_sel_hi:[1,0,1]
	v_pk_fma_f32 v[28:29], v[28:29], 0.5, v[32:33] op_sel_hi:[1,0,1]
	v_pk_fma_f32 v[32:33], v[26:27], 0.5, v[38:39] op_sel_hi:[1,0,1]
	v_cvt_pk_bf16_f32 v26, v34, v35
	v_mul_f32_e32 v34, v34, v34
	v_cvt_pk_bf16_f32 v24, v28, v29
	v_fmac_f32_e32 v34, v28, v28
	v_mul_f32_e32 v28, v35, v35
	v_fmac_f32_e32 v28, v29, v29
	v_mul_f32_e32 v29, v32, v32
	v_add_f32_e32 v28, v34, v28
	v_fmac_f32_e32 v29, v30, v30
	v_add_f32_e32 v28, v29, v28
	v_mul_f32_e32 v29, v33, v33
	v_cvt_pk_bf16_f32 v25, v30, v31
	v_cvt_pk_bf16_f32 v27, v32, v33
	v_fmac_f32_e32 v29, v31, v31
	s_waitcnt vmcnt(6)
	v_lshlrev_b32_e32 v30, 16, v73
	v_and_b32_e32 v31, 0xffff0000, v73
	v_lshlrev_b32_e32 v32, 16, v74
	v_and_b32_e32 v33, 0xffff0000, v74
	v_add_f32_e32 v38, v29, v28
	v_lshlrev_b32_e32 v28, 16, v72
	v_and_b32_e32 v29, 0xffff0000, v72
	v_pk_fma_f32 v[22:23], v[22:23], 0.5, v[30:31] op_sel_hi:[1,0,1]
	v_pk_fma_f32 v[30:31], v[16:17], 0.5, v[32:33] op_sel_hi:[1,0,1]
	v_pk_fma_f32 v[20:21], v[20:21], 0.5, v[28:29] op_sel_hi:[1,0,1]
	v_mul_f32_e32 v16, v30, v30
	v_lshlrev_b32_e32 v34, 16, v75
	v_and_b32_e32 v35, 0xffff0000, v75
	v_fmac_f32_e32 v16, v20, v20
	v_mul_f32_e32 v17, v31, v31
	v_pk_fma_f32 v[28:29], v[18:19], 0.5, v[34:35] op_sel_hi:[1,0,1]
	v_add_f32_e32 v16, v16, v38
	v_fmac_f32_e32 v17, v21, v21
	v_add_f32_e32 v16, v17, v16
	v_mul_f32_e32 v17, v28, v28
	v_fmac_f32_e32 v17, v22, v22
	v_add_f32_e32 v16, v17, v16
	v_mul_f32_e32 v17, v29, v29
	v_fmac_f32_e32 v17, v23, v23
	v_add_f32_e32 v19, v17, v16
	v_mov_b32_e32 v34, v19
	s_nop 1
	v_permlane16_swap_b32_e32 v19, v34
	v_lshl_add_u64 v[36:37], s[94:95], 0, v[98:99]
	v_lshl_add_u64 v[36:37], s[44:45], 1, v[36:37]
	v_lshl_add_u64 v[16:17], v[36:37], 0, s[20:21]
	v_lshl_add_u64 v[32:33], v[16:17], 0, v[160:161]
	s_waitcnt lgkmcnt(0)
	v_add_f32_e32 v16, v19, v34
	v_mov_b32_e32 v17, v16
	s_nop 1
	v_permlane32_swap_b32_e32 v16, v17
	v_cvt_pk_bf16_f32 v18, v20, v21
	v_cvt_pk_bf16_f32 v19, v22, v23
	v_cvt_pk_bf16_f32 v20, v30, v31
	v_cvt_pk_bf16_f32 v21, v28, v29
	global_store_dwordx4 v[32:33], v[24:27], off
	global_store_dwordx4 v[32:33], v[18:21], off offset:256
	s_and_saveexec_b64 s[34:35], s[38:39]
	s_cbranch_execz .LBB0_296
	v_lshlrev_b64 v[18:19], 6, v[94:95]
	v_lshl_add_u64 v[18:19], s[92:93], 0, v[18:19]
	v_lshl_add_u64 v[18:19], s[42:43], 2, v[18:19]
	s_lshl_b32 s48, s71, 2
	s_mov_b32 s49, s21
	v_lshl_add_u64 v[18:19], v[18:19], 0, s[48:49]
	s_waitcnt lgkmcnt(0)
	v_add_f32_e32 v16, v16, v17
	global_store_dword v[18:19], v16, off
.LBB0_296:
	s_or_b64 exec, exec, s[34:35]
	s_waitcnt vmcnt(7)
	v_lshlrev_b32_e32 v18, 16, v69
	v_and_b32_e32 v19, 0xffff0000, v69
	v_lshlrev_b32_e32 v20, 16, v70
	v_and_b32_e32 v21, 0xffff0000, v70
	v_lshlrev_b32_e32 v16, 16, v68
	s_waitcnt lgkmcnt(0)
	v_and_b32_e32 v17, 0xffff0000, v68
	v_lshlrev_b32_e32 v22, 16, v71
	v_and_b32_e32 v23, 0xffff0000, v71
	v_pk_fma_f32 v[14:15], v[14:15], 0.5, v[18:19] op_sel_hi:[1,0,1]
	v_pk_fma_f32 v[18:19], v[8:9], 0.5, v[20:21] op_sel_hi:[1,0,1]
	v_pk_fma_f32 v[12:13], v[12:13], 0.5, v[16:17] op_sel_hi:[1,0,1]
	v_pk_fma_f32 v[16:17], v[10:11], 0.5, v[22:23] op_sel_hi:[1,0,1]
	v_cvt_pk_bf16_f32 v10, v18, v19
	v_mul_f32_e32 v18, v18, v18
	v_cvt_pk_bf16_f32 v8, v12, v13
	v_fmac_f32_e32 v18, v12, v12
	v_mul_f32_e32 v12, v19, v19
	v_fmac_f32_e32 v12, v13, v13
	v_mul_f32_e32 v13, v16, v16
	v_add_f32_e32 v12, v18, v12
	v_fmac_f32_e32 v13, v14, v14
	v_add_f32_e32 v12, v13, v12
	v_mul_f32_e32 v13, v17, v17
	v_cvt_pk_bf16_f32 v9, v14, v15
	v_cvt_pk_bf16_f32 v11, v16, v17
	v_fmac_f32_e32 v13, v15, v15
	s_waitcnt vmcnt(6)
	v_lshlrev_b32_e32 v14, 16, v65
	v_and_b32_e32 v15, 0xffff0000, v65
	v_lshlrev_b32_e32 v16, 16, v66
	v_and_b32_e32 v17, 0xffff0000, v66
	v_add_f32_e32 v22, v13, v12
	v_lshlrev_b32_e32 v12, 16, v64
	v_and_b32_e32 v13, 0xffff0000, v64
	v_pk_fma_f32 v[6:7], v[6:7], 0.5, v[14:15] op_sel_hi:[1,0,1]
	v_pk_fma_f32 v[14:15], v[0:1], 0.5, v[16:17] op_sel_hi:[1,0,1]
	v_pk_fma_f32 v[4:5], v[4:5], 0.5, v[12:13] op_sel_hi:[1,0,1]
	v_mul_f32_e32 v0, v14, v14
	v_lshlrev_b32_e32 v18, 16, v67
	v_and_b32_e32 v19, 0xffff0000, v67
	v_fmac_f32_e32 v0, v4, v4
	v_mul_f32_e32 v1, v15, v15
	v_pk_fma_f32 v[12:13], v[2:3], 0.5, v[18:19] op_sel_hi:[1,0,1]
	v_add_f32_e32 v0, v0, v22
	v_fmac_f32_e32 v1, v5, v5
	v_add_f32_e32 v0, v1, v0
	v_mul_f32_e32 v1, v12, v12
	v_fmac_f32_e32 v1, v6, v6
	v_add_f32_e32 v0, v1, v0
	v_mul_f32_e32 v1, v13, v13
	v_fmac_f32_e32 v1, v7, v7
	v_add_f32_e32 v3, v1, v0
	v_mov_b32_e32 v18, v3
	s_nop 1
	v_permlane16_swap_b32_e32 v3, v18
	v_lshl_add_u64 v[20:21], s[94:95], 0, v[96:97]
	v_lshl_add_u64 v[20:21], s[44:45], 1, v[20:21]
	v_lshl_add_u64 v[0:1], v[20:21], 0, s[20:21]
	v_lshl_add_u64 v[16:17], v[0:1], 0, v[160:161]
	s_waitcnt lgkmcnt(0)
	v_add_f32_e32 v0, v3, v18
	v_mov_b32_e32 v1, v0
	s_nop 1
	v_permlane32_swap_b32_e32 v0, v1
	v_cvt_pk_bf16_f32 v2, v4, v5
	v_cvt_pk_bf16_f32 v3, v6, v7
	v_cvt_pk_bf16_f32 v4, v14, v15
	v_cvt_pk_bf16_f32 v5, v12, v13
	global_store_dwordx4 v[16:17], v[8:11], off
	global_store_dwordx4 v[16:17], v[2:5], off offset:256
	s_and_saveexec_b64 s[34:35], s[38:39]
	s_cbranch_execz .LBB0_269
	v_lshlrev_b64 v[2:3], 6, v[92:93]
	v_lshl_add_u64 v[2:3], s[92:93], 0, v[2:3]
	v_lshl_add_u64 v[2:3], s[42:43], 2, v[2:3]
	s_lshl_b32 s20, s71, 2
	v_lshl_add_u64 v[2:3], v[2:3], 0, s[20:21]
	s_waitcnt lgkmcnt(0)
	v_add_f32_e32 v0, v0, v1
	global_store_dword v[2:3], v0, off
	s_branch .LBB0_269

; __device__ __forceinline__ float bf_lo(unsigned u) { return __uint_as_float(u << 16); }
; __device__ __forceinline__ float bf_hi(unsigned u) { return __uint_as_float(u & 0xffff0000u); }
; __device__ __forceinline__ u32x4 pack8(f32x4 a, f32x4 b) { u32x4 o; o[0] = cvt_pk_bf16(a[0], a[1]); o[1] = cvt_pk_bf16(a[2], a[3]); o[2] = cvt_pk_bf16(b[0], b[1]); o[3] = cvt_pk_bf16(b[2], b[3]); return o; }
;   __device__ __forceinline__ void operator()(const AccT& acc, const Unit& u, int ui, int wr, int wc, int fr, int fq) const {
;     ...
;       u32x4 xh[4][2];
; #pragma unroll
;       for (int m = 0; m < 4; ++m)
; #pragma unroll
;         for (int bj = 0; bj < 2; ++bj)
;           xh[m][bj] = *(const u32x4*)(XB + (size_t)(u.pm * 256 + ai * 128 + wr * 64 + m * 16 + fr) * DM + u.pn * 256 + bj * 128 + wc * 32 + fq * 8);
; #pragma unroll
;       for (int m = 0; m < 4; ++m) {
;         const int row = u.pm * 256 + ai * 128 + wr * 64 + m * 16 + fr; float ss = 0.f;
; #pragma unroll
;         for (int bj = 0; bj < 2; ++bj) {
;           const size_t o = (size_t)row * DM + u.pn * 256 + bj * 128 + wc * 32 + fq * 8;
;           const u32x4 h4 = xh[m][bj];
;           f32x4 y0 = {bf_lo(h4[0]), bf_hi(h4[0]), bf_lo(h4[1]), bf_hi(h4[1])}, y1 = {bf_lo(h4[2]), bf_hi(h4[2]), bf_lo(h4[3]), bf_hi(h4[3])};
;           y0 += acc[ai][bj][m][0] * s; y1 += acc[ai][bj][m][1] * s;
;           *(u32x4*)(XB + o) = pack8(y0, y1);
; #pragma unroll
;           for (int i = 0; i < 4; ++i) ss += y0[i] * y0[i] + y1[i] * y1[i];
;         }
;         ss += __shfl_xor(ss, 16); ss += __shfl_xor(ss, 32);
;         if (fq == 0) RSS[(size_t)row * 16 + u.pn * 4 + wc] = ss;
.Lxa_6:
	v_and_b32_e32 v129, 64, v219
	v_xor_b32_e32 v128, 16, v219
	v_add_u32_e32 v129, 64, v129
	v_cmp_lt_i32_e32 vcc, v128, v129
	s_lshl_b32 s34, s13, 8
	v_lshl_add_u32 v186, s20, 8, v179
	v_cndmask_b32_e32 v128, v219, v128, vcc
	s_ashr_i32 s35, s34, 31
	v_lshlrev_b32_e32 v205, 2, v128
	v_xor_b32_e32 v128, 32, v219
	v_cmp_lt_i32_e32 vcc, v128, v129
	s_lshl_b64 s[48:49], s[34:35], 1
	v_ashrrev_i32_e32 v187, 31, v186
	v_cndmask_b32_e32 v128, v219, v128, vcc
	v_lshl_add_u64 v[188:189], v[180:181], 0, s[48:49]
	v_lshlrev_b64 v[210:211], 11, v[186:187]
	v_lshlrev_b32_e32 v204, 2, v128
	v_lshl_add_u64 v[128:129], v[188:189], 0, v[210:211]
	global_load_dwordx4 v[206:209], v[128:129], off
	global_load_dwordx4 v[152:155], v[128:129], off offset:256
	v_or_b32_e32 v198, 16, v186
	v_ashrrev_i32_e32 v199, 31, v198
	v_or_b32_e32 v192, 32, v186
	v_lshlrev_b64 v[200:201], 11, v[198:199]
	v_ashrrev_i32_e32 v193, 31, v192
	v_or_b32_e32 v190, 48, v186
	v_lshl_add_u64 v[128:129], v[188:189], 0, v[200:201]
	v_lshlrev_b64 v[196:197], 11, v[192:193]
	v_ashrrev_i32_e32 v191, 31, v190
	global_load_dwordx4 v[148:151], v[128:129], off
	global_load_dwordx4 v[144:147], v[128:129], off offset:256
	v_lshl_add_u64 v[128:129], v[188:189], 0, v[196:197]
	v_lshlrev_b64 v[194:195], 11, v[190:191]
	global_load_dwordx4 v[140:143], v[128:129], off
	global_load_dwordx4 v[136:139], v[128:129], off offset:256
	v_lshl_add_u64 v[128:129], v[188:189], 0, v[194:195]
	global_load_dwordx4 v[132:135], v[128:129], off
	s_nop 0
	global_load_dwordx4 v[128:131], v[128:129], off offset:256
	v_lshl_add_u64 v[210:211], s[94:95], 0, v[210:211]
	v_lshl_add_u64 v[210:211], v[210:211], 0, s[48:49]
	s_lshl_b32 s20, s6, 1
	v_lshl_add_u64 v[210:211], v[210:211], 0, s[20:21]
	v_lshlrev_b32_e32 v160, 1, v178
	v_lshl_add_u64 v[210:211], v[210:211], 0, v[160:161]
	s_lshl_b32 vcc_lo, s13, 2
	s_ashr_i32 vcc_hi, vcc_lo, 31
	s_waitcnt vmcnt(0)
	v_lshlrev_b32_e32 v212, 16, v206
	v_and_b32_e32 v213, 0xffff0000, v206
	v_lshlrev_b32_e32 v206, 16, v207
	v_and_b32_e32 v207, 0xffff0000, v207
	v_lshlrev_b32_e32 v222, 16, v208
	v_and_b32_e32 v223, 0xffff0000, v208
	v_lshlrev_b32_e32 v208, 16, v209
	v_and_b32_e32 v209, 0xffff0000, v209
	v_pk_add_f32 v[126:127], v[126:127], v[206:207]
	v_pk_add_f32 v[124:125], v[124:125], v[212:213]
	v_pk_add_f32 v[206:207], v[122:123], v[208:209]
	v_pk_add_f32 v[208:209], v[120:121], v[222:223]
	v_cvt_pk_bf16_f32 v120, v124, v125
	v_cvt_pk_bf16_f32 v121, v126, v127
	v_cvt_pk_bf16_f32 v122, v208, v209
	v_cvt_pk_bf16_f32 v123, v206, v207
	global_store_dwordx4 v[210:211], v[120:123], off
	s_nop 1
	v_mul_f32_e32 v120, v208, v208
	v_mul_f32_e32 v121, v209, v209
	v_fmac_f32_e32 v120, v124, v124
	v_fmac_f32_e32 v121, v125, v125
	v_add_f32_e32 v120, v120, v121
	v_mul_f32_e32 v121, v206, v206
	v_fmac_f32_e32 v121, v126, v126
	v_add_f32_e32 v120, v121, v120
	v_mul_f32_e32 v121, v207, v207
	v_fmac_f32_e32 v121, v127, v127
	v_add_f32_e32 v206, v121, v120
	v_lshlrev_b32_e32 v120, 16, v152
	v_and_b32_e32 v121, 0xffff0000, v152
	v_lshlrev_b32_e32 v122, 16, v153
	v_and_b32_e32 v123, 0xffff0000, v153
	v_lshlrev_b32_e32 v124, 16, v154
	v_and_b32_e32 v125, 0xffff0000, v154
	v_lshlrev_b32_e32 v126, 16, v155
	v_and_b32_e32 v127, 0xffff0000, v155
	v_pk_add_f32 v[118:119], v[118:119], v[122:123]
	v_pk_add_f32 v[116:117], v[116:117], v[120:121]
	v_pk_add_f32 v[120:121], v[114:115], v[126:127]
	v_pk_add_f32 v[122:123], v[112:113], v[124:125]
	v_cvt_pk_bf16_f32 v112, v116, v117
	v_cvt_pk_bf16_f32 v113, v118, v119
	v_cvt_pk_bf16_f32 v114, v122, v123
	v_cvt_pk_bf16_f32 v115, v120, v121
	global_store_dwordx4 v[210:211], v[112:115], off offset:256
	s_nop 1
	v_mul_f32_e32 v112, v122, v122
	v_fmac_f32_e32 v112, v116, v116
	v_mul_f32_e32 v113, v123, v123
	v_add_f32_e32 v112, v112, v206
	v_fmac_f32_e32 v113, v117, v117
	v_add_f32_e32 v112, v113, v112
	v_mul_f32_e32 v113, v120, v120
	v_fmac_f32_e32 v113, v118, v118
	v_add_f32_e32 v112, v113, v112
	v_mul_f32_e32 v113, v121, v121
	v_fmac_f32_e32 v113, v119, v119
	v_add_f32_e32 v112, v113, v112
	v_mov_b32_e32 v113, v112
	s_nop 1
	v_permlane16_swap_b32_e32 v112, v113
	s_waitcnt lgkmcnt(0)
	v_add_f32_e32 v112, v112, v113
	v_mov_b32_e32 v113, v112
	s_nop 1
	v_permlane32_swap_b32_e32 v112, v113
	s_and_saveexec_b64 s[48:49], s[38:39]
	s_cbranch_execz .LBB0_866
	v_lshlrev_b64 v[114:115], 6, v[186:187]
	v_lshl_add_u64 v[114:115], s[92:93], 0, v[114:115]
	v_lshl_add_u64 v[114:115], vcc, 2, v[114:115]
	s_lshl_b32 s68, s71, 2
	s_mov_b32 s69, s21
	v_lshl_add_u64 v[114:115], v[114:115], 0, s[68:69]
	s_waitcnt lgkmcnt(0)
	v_add_f32_e32 v112, v112, v113
	global_store_dword v[114:115], v112, off
; __device__ __forceinline__ float bf_lo(unsigned u) { return __uint_as_float(u << 16); }
; __device__ __forceinline__ float bf_hi(unsigned u) { return __uint_as_float(u & 0xffff0000u); }
; __device__ __forceinline__ u32x4 pack8(f32x4 a, f32x4 b) { u32x4 o; o[0] = cvt_pk_bf16(a[0], a[1]); o[1] = cvt_pk_bf16(a[2], a[3]); o[2] = cvt_pk_bf16(b[0], b[1]); o[3] = cvt_pk_bf16(b[2], b[3]); return o; }
;   __device__ __forceinline__ void operator()(const AccT& acc, const Unit& u, int ui, int wr, int wc, int fr, int fq) const {
;     ...
;       for (int m = 0; m < 4; ++m) {
;         const int row = u.pm * 256 + ai * 128 + wr * 64 + m * 16 + fr; float ss = 0.f;
; #pragma unroll
;         for (int bj = 0; bj < 2; ++bj) {
;           const size_t o = (size_t)row * DM + u.pn * 256 + bj * 128 + wc * 32 + fq * 8;
;           const u32x4 h4 = xh[m][bj];
;           f32x4 y0 = {bf_lo(h4[0]), bf_hi(h4[0]), bf_lo(h4[1]), bf_hi(h4[1])}, y1 = {bf_lo(h4[2]), bf_hi(h4[2]), bf_lo(h4[3]), bf_hi(h4[3])};
;           y0 += acc[ai][bj][m][0] * s; y1 += acc[ai][bj][m][1] * s;
;           *(u32x4*)(XB + o) = pack8(y0, y1);
; #pragma unroll
;           for (int i = 0; i < 4; ++i) ss += y0[i] * y0[i] + y1[i] * y1[i];
;         }
;         ss += __shfl_xor(ss, 16); ss += __shfl_xor(ss, 32);
;         if (fq == 0) RSS[(size_t)row * 16 + u.pn * 4 + wc] = ss;
.LBB0_866:
	s_or_b64 exec, exec, s[48:49]
	v_lshlrev_b32_e32 v114, 16, v149
	v_and_b32_e32 v115, 0xffff0000, v149
	v_lshlrev_b32_e32 v116, 16, v150
	v_and_b32_e32 v117, 0xffff0000, v150
	v_lshlrev_b32_e32 v112, 16, v148
	s_waitcnt lgkmcnt(0)
	v_and_b32_e32 v113, 0xffff0000, v148
	v_lshlrev_b32_e32 v118, 16, v151
	v_and_b32_e32 v119, 0xffff0000, v151
	v_pk_add_f32 v[110:111], v[110:111], v[114:115]
	v_pk_add_f32 v[114:115], v[104:105], v[116:117]
	v_pk_add_f32 v[108:109], v[108:109], v[112:113]
	v_pk_add_f32 v[112:113], v[106:107], v[118:119]
	v_cvt_pk_bf16_f32 v106, v114, v115
	v_mul_f32_e32 v114, v114, v114
	v_cvt_pk_bf16_f32 v104, v108, v109
	v_fmac_f32_e32 v114, v108, v108
	v_mul_f32_e32 v108, v115, v115
	v_fmac_f32_e32 v108, v109, v109
	v_mul_f32_e32 v109, v112, v112
	v_add_f32_e32 v108, v114, v108
	v_fmac_f32_e32 v109, v110, v110
	v_add_f32_e32 v108, v109, v108
	v_mul_f32_e32 v109, v113, v113
	v_cvt_pk_bf16_f32 v105, v110, v111
	v_cvt_pk_bf16_f32 v107, v112, v113
	v_fmac_f32_e32 v109, v111, v111
	v_lshlrev_b32_e32 v110, 16, v145
	v_and_b32_e32 v111, 0xffff0000, v145
	v_lshlrev_b32_e32 v112, 16, v146
	v_and_b32_e32 v113, 0xffff0000, v146
	v_add_f32_e32 v118, v109, v108
	v_lshlrev_b32_e32 v108, 16, v144
	v_and_b32_e32 v109, 0xffff0000, v144
	v_pk_add_f32 v[102:103], v[102:103], v[110:111]
	v_pk_add_f32 v[110:111], v[96:97], v[112:113]
	v_pk_add_f32 v[100:101], v[100:101], v[108:109]
	v_mul_f32_e32 v96, v110, v110
	v_lshlrev_b32_e32 v114, 16, v147
	v_and_b32_e32 v115, 0xffff0000, v147
	v_fmac_f32_e32 v96, v100, v100
	v_mul_f32_e32 v97, v111, v111
	v_pk_add_f32 v[108:109], v[98:99], v[114:115]
	v_add_f32_e32 v96, v96, v118
	v_fmac_f32_e32 v97, v101, v101
	v_add_f32_e32 v96, v97, v96
	v_mul_f32_e32 v97, v108, v108
	v_fmac_f32_e32 v97, v102, v102
	v_add_f32_e32 v96, v97, v96
	v_mul_f32_e32 v97, v109, v109
	v_fmac_f32_e32 v97, v103, v103
	v_add_f32_e32 v99, v97, v96
	v_mov_b32_e32 v114, v99
	s_nop 1
	v_permlane16_swap_b32_e32 v99, v114
	v_lshl_add_u64 v[116:117], s[94:95], 0, v[200:201]
	v_lshl_add_u64 v[116:117], s[34:35], 1, v[116:117]
	v_lshl_add_u64 v[96:97], v[116:117], 0, s[20:21]
	v_lshl_add_u64 v[112:113], v[96:97], 0, v[160:161]
	s_waitcnt lgkmcnt(0)
	v_add_f32_e32 v96, v99, v114
	v_mov_b32_e32 v97, v96
	s_nop 1
	v_permlane32_swap_b32_e32 v96, v97
	v_cvt_pk_bf16_f32 v98, v100, v101
	v_cvt_pk_bf16_f32 v99, v102, v103
	v_cvt_pk_bf16_f32 v100, v110, v111
	v_cvt_pk_bf16_f32 v101, v108, v109
	global_store_dwordx4 v[112:113], v[104:107], off
	global_store_dwordx4 v[112:113], v[98:101], off offset:256
	s_and_saveexec_b64 s[48:49], s[38:39]
	s_cbranch_execz .LBB0_868
	v_lshlrev_b64 v[98:99], 6, v[198:199]
	v_lshl_add_u64 v[98:99], s[92:93], 0, v[98:99]
	v_lshl_add_u64 v[98:99], vcc, 2, v[98:99]
	s_lshl_b32 s68, s71, 2
	s_mov_b32 s69, s21
	v_lshl_add_u64 v[98:99], v[98:99], 0, s[68:69]
	s_waitcnt lgkmcnt(0)
	v_add_f32_e32 v96, v96, v97
	global_store_dword v[98:99], v96, off
.LBB0_868:
	s_or_b64 exec, exec, s[48:49]
	v_lshlrev_b32_e32 v98, 16, v141
	v_and_b32_e32 v99, 0xffff0000, v141
	v_lshlrev_b32_e32 v100, 16, v142
	v_and_b32_e32 v101, 0xffff0000, v142
	v_lshlrev_b32_e32 v96, 16, v140
	s_waitcnt lgkmcnt(0)
	v_and_b32_e32 v97, 0xffff0000, v140
	v_lshlrev_b32_e32 v102, 16, v143
	v_and_b32_e32 v103, 0xffff0000, v143
	v_pk_add_f32 v[94:95], v[94:95], v[98:99]
	v_pk_add_f32 v[98:99], v[88:89], v[100:101]
	v_pk_add_f32 v[92:93], v[92:93], v[96:97]
	v_pk_add_f32 v[96:97], v[90:91], v[102:103]
	v_cvt_pk_bf16_f32 v90, v98, v99
	v_mul_f32_e32 v98, v98, v98
	v_cvt_pk_bf16_f32 v88, v92, v93
	v_fmac_f32_e32 v98, v92, v92
	v_mul_f32_e32 v92, v99, v99
	v_fmac_f32_e32 v92, v93, v93
	v_mul_f32_e32 v93, v96, v96
	v_add_f32_e32 v92, v98, v92
	v_fmac_f32_e32 v93, v94, v94
	v_add_f32_e32 v92, v93, v92
	v_mul_f32_e32 v93, v97, v97
	v_cvt_pk_bf16_f32 v89, v94, v95
	v_cvt_pk_bf16_f32 v91, v96, v97
	v_fmac_f32_e32 v93, v95, v95
	v_lshlrev_b32_e32 v94, 16, v137
	v_and_b32_e32 v95, 0xffff0000, v137
	v_lshlrev_b32_e32 v96, 16, v138
	v_and_b32_e32 v97, 0xffff0000, v138
	v_add_f32_e32 v102, v93, v92
	v_lshlrev_b32_e32 v92, 16, v136
	v_and_b32_e32 v93, 0xffff0000, v136
	v_pk_add_f32 v[86:87], v[86:87], v[94:95]
	v_pk_add_f32 v[94:95], v[80:81], v[96:97]
	v_pk_add_f32 v[84:85], v[84:85], v[92:93]
	v_mul_f32_e32 v80, v94, v94
	v_lshlrev_b32_e32 v98, 16, v139
	v_and_b32_e32 v99, 0xffff0000, v139
	v_fmac_f32_e32 v80, v84, v84
	v_mul_f32_e32 v81, v95, v95
	v_pk_add_f32 v[92:93], v[82:83], v[98:99]
	v_add_f32_e32 v80, v80, v102
	v_fmac_f32_e32 v81, v85, v85
	v_add_f32_e32 v80, v81, v80
	v_mul_f32_e32 v81, v92, v92
	v_fmac_f32_e32 v81, v86, v86
	v_add_f32_e32 v80, v81, v80
	v_mul_f32_e32 v81, v93, v93
	v_fmac_f32_e32 v81, v87, v87
	v_add_f32_e32 v83, v81, v80
	v_mov_b32_e32 v98, v83
	s_nop 1
	v_permlane16_swap_b32_e32 v83, v98
	v_lshl_add_u64 v[100:101], s[94:95], 0, v[196:197]
	v_lshl_add_u64 v[100:101], s[34:35], 1, v[100:101]
	v_lshl_add_u64 v[80:81], v[100:101], 0, s[20:21]
	v_lshl_add_u64 v[96:97], v[80:81], 0, v[160:161]
	s_waitcnt lgkmcnt(0)
	v_add_f32_e32 v80, v83, v98
	v_mov_b32_e32 v81, v80
	s_nop 1
	v_permlane32_swap_b32_e32 v80, v81
	v_cvt_pk_bf16_f32 v82, v84, v85
	v_cvt_pk_bf16_f32 v83, v86, v87
	v_cvt_pk_bf16_f32 v84, v94, v95
	v_cvt_pk_bf16_f32 v85, v92, v93
	global_store_dwordx4 v[96:97], v[88:91], off
	global_store_dwordx4 v[96:97], v[82:85], off offset:256
	s_and_saveexec_b64 s[48:49], s[38:39]
	s_cbranch_execz .LBB0_870
	v_lshlrev_b64 v[82:83], 6, v[192:193]
	v_lshl_add_u64 v[82:83], s[92:93], 0, v[82:83]
	v_lshl_add_u64 v[82:83], vcc, 2, v[82:83]
	s_lshl_b32 s68, s71, 2
	s_mov_b32 s69, s21
	v_lshl_add_u64 v[82:83], v[82:83], 0, s[68:69]
	s_waitcnt lgkmcnt(0)
	v_add_f32_e32 v80, v80, v81
	global_store_dword v[82:83], v80, off
; __device__ __forceinline__ float bf_lo(unsigned u) { return __uint_as_float(u << 16); }
; __device__ __forceinline__ float bf_hi(unsigned u) { return __uint_as_float(u & 0xffff0000u); }
; __device__ __forceinline__ u32x4 pack8(f32x4 a, f32x4 b) { u32x4 o; o[0] = cvt_pk_bf16(a[0], a[1]); o[1] = cvt_pk_bf16(a[2], a[3]); o[2] = cvt_pk_bf16(b[0], b[1]); o[3] = cvt_pk_bf16(b[2], b[3]); return o; }
;   __device__ __forceinline__ void operator()(const AccT& acc, const Unit& u, int ui, int wr, int wc, int fr, int fq) const {
;     ...
;           xh[m][bj] = *(const u32x4*)(XB + (size_t)(u.pm * 256 + ai * 128 + wr * 64 + m * 16 + fr) * DM + u.pn * 256 + bj * 128 + wc * 32 + fq * 8);
; #pragma unroll
;       for (int m = 0; m < 4; ++m) {
;         const int row = u.pm * 256 + ai * 128 + wr * 64 + m * 16 + fr; float ss = 0.f;
; #pragma unroll
;         for (int bj = 0; bj < 2; ++bj) {
;           const size_t o = (size_t)row * DM + u.pn * 256 + bj * 128 + wc * 32 + fq * 8;
;           const u32x4 h4 = xh[m][bj];
;           f32x4 y0 = {bf_lo(h4[0]), bf_hi(h4[0]), bf_lo(h4[1]), bf_hi(h4[1])}, y1 = {bf_lo(h4[2]), bf_hi(h4[2]), bf_lo(h4[3]), bf_hi(h4[3])};
;           y0 += acc[ai][bj][m][0] * s; y1 += acc[ai][bj][m][1] * s;
;           *(u32x4*)(XB + o) = pack8(y0, y1);
; #pragma unroll
;           for (int i = 0; i < 4; ++i) ss += y0[i] * y0[i] + y1[i] * y1[i];
;         }
;         ss += __shfl_xor(ss, 16); ss += __shfl_xor(ss, 32);
;         if (fq == 0) RSS[(size_t)row * 16 + u.pn * 4 + wc] = ss;
.LBB0_870:
	s_or_b64 exec, exec, s[48:49]
	v_lshlrev_b32_e32 v82, 16, v133
	v_and_b32_e32 v83, 0xffff0000, v133
	v_lshlrev_b32_e32 v84, 16, v134
	v_and_b32_e32 v85, 0xffff0000, v134
	v_lshlrev_b32_e32 v80, 16, v132
	s_waitcnt lgkmcnt(0)
	v_and_b32_e32 v81, 0xffff0000, v132
	v_lshlrev_b32_e32 v86, 16, v135
	v_and_b32_e32 v87, 0xffff0000, v135
	v_pk_add_f32 v[78:79], v[78:79], v[82:83]
	v_pk_add_f32 v[82:83], v[72:73], v[84:85]
	v_pk_add_f32 v[76:77], v[76:77], v[80:81]
	v_pk_add_f32 v[80:81], v[74:75], v[86:87]
	v_cvt_pk_bf16_f32 v74, v82, v83
	v_mul_f32_e32 v82, v82, v82
	v_cvt_pk_bf16_f32 v72, v76, v77
	v_fmac_f32_e32 v82, v76, v76
	v_mul_f32_e32 v76, v83, v83
	v_fmac_f32_e32 v76, v77, v77
	v_mul_f32_e32 v77, v80, v80
	v_add_f32_e32 v76, v82, v76
	v_fmac_f32_e32 v77, v78, v78
	v_add_f32_e32 v76, v77, v76
	v_mul_f32_e32 v77, v81, v81
	v_cvt_pk_bf16_f32 v73, v78, v79
	v_cvt_pk_bf16_f32 v75, v80, v81
	v_fmac_f32_e32 v77, v79, v79
	v_lshlrev_b32_e32 v78, 16, v129
	v_and_b32_e32 v79, 0xffff0000, v129
	v_lshlrev_b32_e32 v80, 16, v130
	v_and_b32_e32 v81, 0xffff0000, v130
	v_add_f32_e32 v86, v77, v76
	v_lshlrev_b32_e32 v76, 16, v128
	v_and_b32_e32 v77, 0xffff0000, v128
	v_pk_add_f32 v[70:71], v[70:71], v[78:79]
	v_pk_add_f32 v[78:79], v[64:65], v[80:81]
	v_pk_add_f32 v[68:69], v[68:69], v[76:77]
	v_mul_f32_e32 v64, v78, v78
	v_lshlrev_b32_e32 v82, 16, v131
	v_and_b32_e32 v83, 0xffff0000, v131
	v_fmac_f32_e32 v64, v68, v68
	v_mul_f32_e32 v65, v79, v79
	v_pk_add_f32 v[76:77], v[66:67], v[82:83]
	v_add_f32_e32 v64, v64, v86
	v_fmac_f32_e32 v65, v69, v69
	v_add_f32_e32 v64, v65, v64
	v_mul_f32_e32 v65, v76, v76
	v_fmac_f32_e32 v65, v70, v70
	v_add_f32_e32 v64, v65, v64
	v_mul_f32_e32 v65, v77, v77
	v_fmac_f32_e32 v65, v71, v71
	v_add_f32_e32 v67, v65, v64
	v_mov_b32_e32 v82, v67
	s_nop 1
	v_permlane16_swap_b32_e32 v67, v82
	v_lshl_add_u64 v[84:85], s[94:95], 0, v[194:195]
	v_lshl_add_u64 v[84:85], s[34:35], 1, v[84:85]
	v_lshl_add_u64 v[64:65], v[84:85], 0, s[20:21]
	v_lshl_add_u64 v[80:81], v[64:65], 0, v[160:161]
	s_waitcnt lgkmcnt(0)
	v_add_f32_e32 v64, v67, v82
	v_mov_b32_e32 v65, v64
	s_nop 1
	v_permlane32_swap_b32_e32 v64, v65
	v_cvt_pk_bf16_f32 v66, v68, v69
	v_cvt_pk_bf16_f32 v67, v70, v71
	v_cvt_pk_bf16_f32 v68, v78, v79
	v_cvt_pk_bf16_f32 v69, v76, v77
	global_store_dwordx4 v[80:81], v[72:75], off
	global_store_dwordx4 v[80:81], v[66:69], off offset:256
	s_and_saveexec_b64 s[48:49], s[38:39]
	s_cbranch_execz .LBB0_872
	v_lshlrev_b64 v[66:67], 6, v[190:191]
	v_lshl_add_u64 v[66:67], s[92:93], 0, v[66:67]
	v_lshl_add_u64 v[66:67], vcc, 2, v[66:67]
	s_lshl_b32 s68, s71, 2
	s_mov_b32 s69, s21
	v_lshl_add_u64 v[66:67], v[66:67], 0, s[68:69]
	s_waitcnt lgkmcnt(0)
	v_add_f32_e32 v64, v64, v65
	global_store_dword v[66:67], v64, off
.LBB0_872:
	s_or_b64 exec, exec, s[48:49]
	v_add_u32_e32 v104, 0x80, v186
	v_ashrrev_i32_e32 v105, 31, v104
	v_lshlrev_b64 v[110:111], 11, v[104:105]
	s_waitcnt lgkmcnt(0)
	v_lshl_add_u64 v[64:65], v[188:189], 0, v[110:111]
	global_load_dwordx4 v[106:109], v[64:65], off
	global_load_dwordx4 v[88:91], v[64:65], off offset:256
	v_add_u32_e32 v100, 0x90, v186
	v_ashrrev_i32_e32 v101, 31, v100
	v_add_u32_e32 v94, 0xa0, v186
	v_lshlrev_b64 v[102:103], 11, v[100:101]
	v_ashrrev_i32_e32 v95, 31, v94
	v_add_u32_e32 v92, 0xb0, v186
	v_lshl_add_u64 v[64:65], v[188:189], 0, v[102:103]
	v_lshlrev_b64 v[98:99], 11, v[94:95]
	v_ashrrev_i32_e32 v93, 31, v92
	global_load_dwordx4 v[84:87], v[64:65], off
	global_load_dwordx4 v[80:83], v[64:65], off offset:256
	v_lshl_add_u64 v[64:65], v[188:189], 0, v[98:99]
	v_lshlrev_b64 v[96:97], 11, v[92:93]
	global_load_dwordx4 v[76:79], v[64:65], off
	global_load_dwordx4 v[72:75], v[64:65], off offset:256
	v_lshl_add_u64 v[64:65], v[188:189], 0, v[96:97]
	global_load_dwordx4 v[68:71], v[64:65], off
	s_nop 0
	global_load_dwordx4 v[64:67], v[64:65], off offset:256
	v_lshl_add_u64 v[110:111], s[94:95], 0, v[110:111]
	v_lshl_add_u64 v[110:111], s[34:35], 1, v[110:111]
	v_lshl_add_u64 v[110:111], v[110:111], 0, s[20:21]
	v_lshl_add_u64 v[110:111], v[110:111], 0, v[160:161]
	s_waitcnt vmcnt(7)
	v_lshlrev_b32_e32 v112, 16, v106
	v_and_b32_e32 v113, 0xffff0000, v106
	v_lshlrev_b32_e32 v106, 16, v107
	v_and_b32_e32 v107, 0xffff0000, v107
	v_lshlrev_b32_e32 v114, 16, v108
	v_and_b32_e32 v115, 0xffff0000, v108
	v_lshlrev_b32_e32 v108, 16, v109
	v_and_b32_e32 v109, 0xffff0000, v109
	v_pk_add_f32 v[62:63], v[62:63], v[106:107]
	v_pk_add_f32 v[60:61], v[60:61], v[112:113]
	v_pk_add_f32 v[106:107], v[58:59], v[108:109]
	v_pk_add_f32 v[108:109], v[56:57], v[114:115]
	v_cvt_pk_bf16_f32 v56, v60, v61
	v_cvt_pk_bf16_f32 v57, v62, v63
	v_cvt_pk_bf16_f32 v58, v108, v109
	v_cvt_pk_bf16_f32 v59, v106, v107
	global_store_dwordx4 v[110:111], v[56:59], off
	s_nop 1
	v_mul_f32_e32 v56, v108, v108
	v_mul_f32_e32 v57, v109, v109
	v_fmac_f32_e32 v56, v60, v60
	v_fmac_f32_e32 v57, v61, v61
	v_add_f32_e32 v56, v56, v57
	v_mul_f32_e32 v57, v106, v106
	v_fmac_f32_e32 v57, v62, v62
	v_add_f32_e32 v56, v57, v56
	v_mul_f32_e32 v57, v107, v107
	v_fmac_f32_e32 v57, v63, v63
	v_add_f32_e32 v106, v57, v56
	s_waitcnt vmcnt(7)
	v_lshlrev_b32_e32 v56, 16, v88
	v_and_b32_e32 v57, 0xffff0000, v88
	v_lshlrev_b32_e32 v58, 16, v89
	v_and_b32_e32 v59, 0xffff0000, v89
	v_lshlrev_b32_e32 v60, 16, v90
	v_and_b32_e32 v61, 0xffff0000, v90
	v_lshlrev_b32_e32 v62, 16, v91
	v_and_b32_e32 v63, 0xffff0000, v91
	v_pk_add_f32 v[54:55], v[54:55], v[58:59]
	v_pk_add_f32 v[52:53], v[52:53], v[56:57]
	v_pk_add_f32 v[56:57], v[50:51], v[62:63]
	v_pk_add_f32 v[58:59], v[48:49], v[60:61]
	v_cvt_pk_bf16_f32 v48, v52, v53
	v_cvt_pk_bf16_f32 v49, v54, v55
	v_cvt_pk_bf16_f32 v50, v58, v59
	v_cvt_pk_bf16_f32 v51, v56, v57
	global_store_dwordx4 v[110:111], v[48:51], off offset:256
	s_nop 1
	v_mul_f32_e32 v48, v58, v58
	v_fmac_f32_e32 v48, v52, v52
	v_mul_f32_e32 v49, v59, v59
	v_add_f32_e32 v48, v48, v106
	v_fmac_f32_e32 v49, v53, v53
	v_add_f32_e32 v48, v49, v48
	v_mul_f32_e32 v49, v56, v56
	v_fmac_f32_e32 v49, v54, v54
	v_add_f32_e32 v48, v49, v48
	v_mul_f32_e32 v49, v57, v57
	v_fmac_f32_e32 v49, v55, v55
	v_add_f32_e32 v48, v49, v48
	v_mov_b32_e32 v49, v48
	s_nop 1
	v_permlane16_swap_b32_e32 v48, v49
	s_waitcnt lgkmcnt(0)
	v_add_f32_e32 v48, v48, v49
	v_mov_b32_e32 v49, v48
	s_nop 1
	v_permlane32_swap_b32_e32 v48, v49
	s_and_saveexec_b64 s[48:49], s[38:39]
	s_cbranch_execz .LBB0_874
	v_lshlrev_b64 v[50:51], 6, v[104:105]
	v_lshl_add_u64 v[50:51], s[92:93], 0, v[50:51]
	v_lshl_add_u64 v[50:51], vcc, 2, v[50:51]
	s_lshl_b32 s68, s71, 2
	s_mov_b32 s69, s21
	v_lshl_add_u64 v[50:51], v[50:51], 0, s[68:69]
	s_waitcnt lgkmcnt(0)
	v_add_f32_e32 v48, v48, v49
	global_store_dword v[50:51], v48, off
; __device__ __forceinline__ float bf_lo(unsigned u) { return __uint_as_float(u << 16); }
; __device__ __forceinline__ float bf_hi(unsigned u) { return __uint_as_float(u & 0xffff0000u); }
; __device__ __forceinline__ u32x4 pack8(f32x4 a, f32x4 b) { u32x4 o; o[0] = cvt_pk_bf16(a[0], a[1]); o[1] = cvt_pk_bf16(a[2], a[3]); o[2] = cvt_pk_bf16(b[0], b[1]); o[3] = cvt_pk_bf16(b[2], b[3]); return o; }
;   __device__ __forceinline__ void operator()(const AccT& acc, const Unit& u, int ui, int wr, int wc, int fr, int fq) const {
;     ...
;       for (int m = 0; m < 4; ++m) {
;         const int row = u.pm * 256 + ai * 128 + wr * 64 + m * 16 + fr; float ss = 0.f;
; #pragma unroll
;         for (int bj = 0; bj < 2; ++bj) {
;           const size_t o = (size_t)row * DM + u.pn * 256 + bj * 128 + wc * 32 + fq * 8;
;           const u32x4 h4 = xh[m][bj];
;           f32x4 y0 = {bf_lo(h4[0]), bf_hi(h4[0]), bf_lo(h4[1]), bf_hi(h4[1])}, y1 = {bf_lo(h4[2]), bf_hi(h4[2]), bf_lo(h4[3]), bf_hi(h4[3])};
;           y0 += acc[ai][bj][m][0] * s; y1 += acc[ai][bj][m][1] * s;
;           *(u32x4*)(XB + o) = pack8(y0, y1);
; #pragma unroll
;           for (int i = 0; i < 4; ++i) ss += y0[i] * y0[i] + y1[i] * y1[i];
;         }
;         ss += __shfl_xor(ss, 16); ss += __shfl_xor(ss, 32);
;         if (fq == 0) RSS[(size_t)row * 16 + u.pn * 4 + wc] = ss;
.LBB0_874:
	s_or_b64 exec, exec, s[48:49]
	s_waitcnt vmcnt(7)
	v_lshlrev_b32_e32 v50, 16, v85
	v_and_b32_e32 v51, 0xffff0000, v85
	v_lshlrev_b32_e32 v52, 16, v86
	v_and_b32_e32 v53, 0xffff0000, v86
	v_lshlrev_b32_e32 v48, 16, v84
	s_waitcnt lgkmcnt(0)
	v_and_b32_e32 v49, 0xffff0000, v84
	v_lshlrev_b32_e32 v54, 16, v87
	v_and_b32_e32 v55, 0xffff0000, v87
	v_pk_add_f32 v[46:47], v[46:47], v[50:51]
	v_pk_add_f32 v[50:51], v[40:41], v[52:53]
	v_pk_add_f32 v[44:45], v[44:45], v[48:49]
	v_pk_add_f32 v[48:49], v[42:43], v[54:55]
	v_cvt_pk_bf16_f32 v42, v50, v51
	v_mul_f32_e32 v50, v50, v50
	v_cvt_pk_bf16_f32 v40, v44, v45
	v_fmac_f32_e32 v50, v44, v44
	v_mul_f32_e32 v44, v51, v51
	v_fmac_f32_e32 v44, v45, v45
	v_mul_f32_e32 v45, v48, v48
	v_add_f32_e32 v44, v50, v44
	v_fmac_f32_e32 v45, v46, v46
	v_add_f32_e32 v44, v45, v44
	v_mul_f32_e32 v45, v49, v49
	v_cvt_pk_bf16_f32 v41, v46, v47
	v_cvt_pk_bf16_f32 v43, v48, v49
	v_fmac_f32_e32 v45, v47, v47
	s_waitcnt vmcnt(6)
	v_lshlrev_b32_e32 v46, 16, v81
	v_and_b32_e32 v47, 0xffff0000, v81
	v_lshlrev_b32_e32 v48, 16, v82
	v_and_b32_e32 v49, 0xffff0000, v82
	v_add_f32_e32 v54, v45, v44
	v_lshlrev_b32_e32 v44, 16, v80
	v_and_b32_e32 v45, 0xffff0000, v80
	v_pk_add_f32 v[38:39], v[38:39], v[46:47]
	v_pk_add_f32 v[46:47], v[32:33], v[48:49]
	v_pk_add_f32 v[36:37], v[36:37], v[44:45]
	v_mul_f32_e32 v32, v46, v46
	v_lshlrev_b32_e32 v50, 16, v83
	v_and_b32_e32 v51, 0xffff0000, v83
	v_fmac_f32_e32 v32, v36, v36
	v_mul_f32_e32 v33, v47, v47
	v_pk_add_f32 v[44:45], v[34:35], v[50:51]
	v_add_f32_e32 v32, v32, v54
	v_fmac_f32_e32 v33, v37, v37
	v_add_f32_e32 v32, v33, v32
	v_mul_f32_e32 v33, v44, v44
	v_fmac_f32_e32 v33, v38, v38
	v_add_f32_e32 v32, v33, v32
	v_mul_f32_e32 v33, v45, v45
	v_fmac_f32_e32 v33, v39, v39
	v_add_f32_e32 v35, v33, v32
	v_mov_b32_e32 v50, v35
	s_nop 1
	v_permlane16_swap_b32_e32 v35, v50
	v_lshl_add_u64 v[52:53], s[94:95], 0, v[102:103]
	v_lshl_add_u64 v[52:53], s[34:35], 1, v[52:53]
	v_lshl_add_u64 v[32:33], v[52:53], 0, s[20:21]
	v_lshl_add_u64 v[48:49], v[32:33], 0, v[160:161]
	s_waitcnt lgkmcnt(0)
	v_add_f32_e32 v32, v35, v50
	v_mov_b32_e32 v33, v32
	s_nop 1
	v_permlane32_swap_b32_e32 v32, v33
	v_cvt_pk_bf16_f32 v34, v36, v37
	v_cvt_pk_bf16_f32 v35, v38, v39
	v_cvt_pk_bf16_f32 v36, v46, v47
	v_cvt_pk_bf16_f32 v37, v44, v45
	global_store_dwordx4 v[48:49], v[40:43], off
	global_store_dwordx4 v[48:49], v[34:37], off offset:256
	s_and_saveexec_b64 s[48:49], s[38:39]
	s_cbranch_execz .LBB0_876
	v_lshlrev_b64 v[34:35], 6, v[100:101]
	v_lshl_add_u64 v[34:35], s[92:93], 0, v[34:35]
	v_lshl_add_u64 v[34:35], vcc, 2, v[34:35]
	s_lshl_b32 s68, s71, 2
	s_mov_b32 s69, s21
	v_lshl_add_u64 v[34:35], v[34:35], 0, s[68:69]
	s_waitcnt lgkmcnt(0)
	v_add_f32_e32 v32, v32, v33
	global_store_dword v[34:35], v32, off
; __device__ __forceinline__ float bf_lo(unsigned u) { return __uint_as_float(u << 16); }
; __device__ __forceinline__ float bf_hi(unsigned u) { return __uint_as_float(u & 0xffff0000u); }
; __device__ __forceinline__ u32x4 pack8(f32x4 a, f32x4 b) { u32x4 o; o[0] = cvt_pk_bf16(a[0], a[1]); o[1] = cvt_pk_bf16(a[2], a[3]); o[2] = cvt_pk_bf16(b[0], b[1]); o[3] = cvt_pk_bf16(b[2], b[3]); return o; }
;   __device__ __forceinline__ void operator()(const AccT& acc, const Unit& u, int ui, int wr, int wc, int fr, int fq) const {
;     ...
;       for (int m = 0; m < 4; ++m) {
;         const int row = u.pm * 256 + ai * 128 + wr * 64 + m * 16 + fr; float ss = 0.f;
; #pragma unroll
;         for (int bj = 0; bj < 2; ++bj) {
;           const size_t o = (size_t)row * DM + u.pn * 256 + bj * 128 + wc * 32 + fq * 8;
;           const u32x4 h4 = xh[m][bj];
;           f32x4 y0 = {bf_lo(h4[0]), bf_hi(h4[0]), bf_lo(h4[1]), bf_hi(h4[1])}, y1 = {bf_lo(h4[2]), bf_hi(h4[2]), bf_lo(h4[3]), bf_hi(h4[3])};
;           y0 += acc[ai][bj][m][0] * s; y1 += acc[ai][bj][m][1] * s;
;           *(u32x4*)(XB + o) = pack8(y0, y1);
; #pragma unroll
;           for (int i = 0; i < 4; ++i) ss += y0[i] * y0[i] + y1[i] * y1[i];
;         }
;         ss += __shfl_xor(ss, 16); ss += __shfl_xor(ss, 32);
;         if (fq == 0) RSS[(size_t)row * 16 + u.pn * 4 + wc] = ss;
;       }
.LBB0_876:
	s_or_b64 exec, exec, s[48:49]
	s_waitcnt vmcnt(7)
	v_lshlrev_b32_e32 v34, 16, v77
	v_and_b32_e32 v35, 0xffff0000, v77
	v_lshlrev_b32_e32 v36, 16, v78
	v_and_b32_e32 v37, 0xffff0000, v78
	v_lshlrev_b32_e32 v32, 16, v76
	s_waitcnt lgkmcnt(0)
	v_and_b32_e32 v33, 0xffff0000, v76
	v_lshlrev_b32_e32 v38, 16, v79
	v_and_b32_e32 v39, 0xffff0000, v79
	v_pk_add_f32 v[30:31], v[30:31], v[34:35]
	v_pk_add_f32 v[34:35], v[24:25], v[36:37]
	v_pk_add_f32 v[28:29], v[28:29], v[32:33]
	v_pk_add_f32 v[32:33], v[26:27], v[38:39]
	v_cvt_pk_bf16_f32 v26, v34, v35
	v_mul_f32_e32 v34, v34, v34
	v_cvt_pk_bf16_f32 v24, v28, v29
	v_fmac_f32_e32 v34, v28, v28
	v_mul_f32_e32 v28, v35, v35
	v_fmac_f32_e32 v28, v29, v29
	v_mul_f32_e32 v29, v32, v32
	v_add_f32_e32 v28, v34, v28
	v_fmac_f32_e32 v29, v30, v30
	v_add_f32_e32 v28, v29, v28
	v_mul_f32_e32 v29, v33, v33
	v_cvt_pk_bf16_f32 v25, v30, v31
	v_cvt_pk_bf16_f32 v27, v32, v33
	v_fmac_f32_e32 v29, v31, v31
	s_waitcnt vmcnt(6)
	v_lshlrev_b32_e32 v30, 16, v73
	v_and_b32_e32 v31, 0xffff0000, v73
	v_lshlrev_b32_e32 v32, 16, v74
	v_and_b32_e32 v33, 0xffff0000, v74
	v_add_f32_e32 v38, v29, v28
	v_lshlrev_b32_e32 v28, 16, v72
	v_and_b32_e32 v29, 0xffff0000, v72
	v_pk_add_f32 v[22:23], v[22:23], v[30:31]
	v_pk_add_f32 v[30:31], v[16:17], v[32:33]
	v_pk_add_f32 v[20:21], v[20:21], v[28:29]
	v_mul_f32_e32 v16, v30, v30
	v_lshlrev_b32_e32 v34, 16, v75
	v_and_b32_e32 v35, 0xffff0000, v75
	v_fmac_f32_e32 v16, v20, v20
	v_mul_f32_e32 v17, v31, v31
	v_pk_add_f32 v[28:29], v[18:19], v[34:35]
	v_add_f32_e32 v16, v16, v38
	v_fmac_f32_e32 v17, v21, v21
	v_add_f32_e32 v16, v17, v16
	v_mul_f32_e32 v17, v28, v28
	v_fmac_f32_e32 v17, v22, v22
	v_add_f32_e32 v16, v17, v16
	v_mul_f32_e32 v17, v29, v29
	v_fmac_f32_e32 v17, v23, v23
	v_add_f32_e32 v19, v17, v16
	v_mov_b32_e32 v34, v19
	s_nop 1
	v_permlane16_swap_b32_e32 v19, v34
	v_lshl_add_u64 v[36:37], s[94:95], 0, v[98:99]
	v_lshl_add_u64 v[36:37], s[34:35], 1, v[36:37]
	v_lshl_add_u64 v[16:17], v[36:37], 0, s[20:21]
	v_lshl_add_u64 v[32:33], v[16:17], 0, v[160:161]
	s_waitcnt lgkmcnt(0)
	v_add_f32_e32 v16, v19, v34
	v_mov_b32_e32 v17, v16
	s_nop 1
	v_permlane32_swap_b32_e32 v16, v17
	v_cvt_pk_bf16_f32 v18, v20, v21
	v_cvt_pk_bf16_f32 v19, v22, v23
	v_cvt_pk_bf16_f32 v20, v30, v31
	v_cvt_pk_bf16_f32 v21, v28, v29
	global_store_dwordx4 v[32:33], v[24:27], off
	global_store_dwordx4 v[32:33], v[18:21], off offset:256
	s_and_saveexec_b64 s[48:49], s[38:39]
	s_cbranch_execz .LBB0_878
	v_lshlrev_b64 v[18:19], 6, v[94:95]
	v_lshl_add_u64 v[18:19], s[92:93], 0, v[18:19]
	v_lshl_add_u64 v[18:19], vcc, 2, v[18:19]
	s_lshl_b32 s68, s71, 2
	s_mov_b32 s69, s21
	v_lshl_add_u64 v[18:19], v[18:19], 0, s[68:69]
	s_waitcnt lgkmcnt(0)
	v_add_f32_e32 v16, v16, v17
	global_store_dword v[18:19], v16, off
.LBB0_878:
	s_or_b64 exec, exec, s[48:49]
	s_waitcnt vmcnt(7)
	v_lshlrev_b32_e32 v18, 16, v69
	v_and_b32_e32 v19, 0xffff0000, v69
	v_lshlrev_b32_e32 v20, 16, v70
	v_and_b32_e32 v21, 0xffff0000, v70
	v_lshlrev_b32_e32 v16, 16, v68
	s_waitcnt lgkmcnt(0)
	v_and_b32_e32 v17, 0xffff0000, v68
	v_lshlrev_b32_e32 v22, 16, v71
	v_and_b32_e32 v23, 0xffff0000, v71
	v_pk_add_f32 v[14:15], v[14:15], v[18:19]
	v_pk_add_f32 v[18:19], v[8:9], v[20:21]
	v_pk_add_f32 v[12:13], v[12:13], v[16:17]
	v_pk_add_f32 v[16:17], v[10:11], v[22:23]
	v_cvt_pk_bf16_f32 v10, v18, v19
	v_mul_f32_e32 v18, v18, v18
	v_cvt_pk_bf16_f32 v8, v12, v13
	v_fmac_f32_e32 v18, v12, v12
	v_mul_f32_e32 v12, v19, v19
	v_fmac_f32_e32 v12, v13, v13
	v_mul_f32_e32 v13, v16, v16
	v_add_f32_e32 v12, v18, v12
	v_fmac_f32_e32 v13, v14, v14
	v_add_f32_e32 v12, v13, v12
	v_mul_f32_e32 v13, v17, v17
	v_cvt_pk_bf16_f32 v9, v14, v15
	v_cvt_pk_bf16_f32 v11, v16, v17
	v_fmac_f32_e32 v13, v15, v15
	s_waitcnt vmcnt(6)
	v_lshlrev_b32_e32 v14, 16, v65
	v_and_b32_e32 v15, 0xffff0000, v65
	v_lshlrev_b32_e32 v16, 16, v66
	v_and_b32_e32 v17, 0xffff0000, v66
	v_add_f32_e32 v22, v13, v12
	v_lshlrev_b32_e32 v12, 16, v64
	v_and_b32_e32 v13, 0xffff0000, v64
	v_pk_add_f32 v[6:7], v[6:7], v[14:15]
	v_pk_add_f32 v[14:15], v[0:1], v[16:17]
	v_pk_add_f32 v[4:5], v[4:5], v[12:13]
	v_mul_f32_e32 v0, v14, v14
	v_lshlrev_b32_e32 v18, 16, v67
	v_and_b32_e32 v19, 0xffff0000, v67
	v_fmac_f32_e32 v0, v4, v4
	v_mul_f32_e32 v1, v15, v15
	v_pk_add_f32 v[12:13], v[2:3], v[18:19]
	v_add_f32_e32 v0, v0, v22
	v_fmac_f32_e32 v1, v5, v5
	v_add_f32_e32 v0, v1, v0
	v_mul_f32_e32 v1, v12, v12
	v_fmac_f32_e32 v1, v6, v6
	v_add_f32_e32 v0, v1, v0
	v_mul_f32_e32 v1, v13, v13
	v_fmac_f32_e32 v1, v7, v7
	v_add_f32_e32 v3, v1, v0
	v_mov_b32_e32 v18, v3
	s_nop 1
	v_permlane16_swap_b32_e32 v3, v18
	v_lshl_add_u64 v[20:21], s[94:95], 0, v[96:97]
	v_lshl_add_u64 v[20:21], s[34:35], 1, v[20:21]
	v_lshl_add_u64 v[0:1], v[20:21], 0, s[20:21]
	v_lshl_add_u64 v[16:17], v[0:1], 0, v[160:161]
	s_waitcnt lgkmcnt(0)
	v_add_f32_e32 v0, v3, v18
	v_mov_b32_e32 v1, v0
	s_nop 1
	v_permlane32_swap_b32_e32 v0, v1
	v_cvt_pk_bf16_f32 v2, v4, v5
	v_cvt_pk_bf16_f32 v3, v6, v7
	v_cvt_pk_bf16_f32 v4, v14, v15
	v_cvt_pk_bf16_f32 v5, v12, v13
	global_store_dwordx4 v[16:17], v[8:11], off
	global_store_dwordx4 v[16:17], v[2:5], off offset:256
	s_and_saveexec_b64 s[34:35], s[38:39]
	s_cbranch_execz .LBB0_855
	v_lshlrev_b64 v[2:3], 6, v[92:93]
	v_lshl_add_u64 v[2:3], s[92:93], 0, v[2:3]
	v_lshl_add_u64 v[2:3], vcc, 2, v[2:3]
	s_lshl_b32 s20, s71, 2
	v_lshl_add_u64 v[2:3], v[2:3], 0, s[20:21]
	s_waitcnt lgkmcnt(0)
	v_add_f32_e32 v0, v0, v1
	global_store_dword v[2:3], v0, off
	s_branch .LBB0_855

; __device__ __forceinline__ float bf_lo(unsigned u) { return __uint_as_float(u << 16); }
; __device__ __forceinline__ float bf_hi(unsigned u) { return __uint_as_float(u & 0xffff0000u); }
; __device__ __forceinline__ u32x4 pack8(f32x4 a, f32x4 b) { u32x4 o; o[0] = cvt_pk_bf16(a[0], a[1]); o[1] = cvt_pk_bf16(a[2], a[3]); o[2] = cvt_pk_bf16(b[0], b[1]); o[3] = cvt_pk_bf16(b[2], b[3]); return o; }
;   __device__ __forceinline__ void operator()(const AccT& acc, const Unit& u, int ui, int wr, int wc, int fr, int fq) const {
;     ...
;       u32x4 xh[4][2];
; #pragma unroll
;       for (int m = 0; m < 4; ++m)
; #pragma unroll
;         for (int bj = 0; bj < 2; ++bj)
;           xh[m][bj] = *(const u32x4*)(XB + (size_t)(u.pm * 256 + ai * 128 + wr * 64 + m * 16 + fr) * DM + u.pn * 256 + bj * 128 + wc * 32 + fq * 8);
; #pragma unroll
;       for (int m = 0; m < 4; ++m) {
;         const int row = u.pm * 256 + ai * 128 + wr * 64 + m * 16 + fr; float ss = 0.f;
; #pragma unroll
;         for (int bj = 0; bj < 2; ++bj) {
;           const size_t o = (size_t)row * DM + u.pn * 256 + bj * 128 + wc * 32 + fq * 8;
;           const u32x4 h4 = xh[m][bj];
;           f32x4 y0 = {bf_lo(h4[0]), bf_hi(h4[0]), bf_lo(h4[1]), bf_hi(h4[1])}, y1 = {bf_lo(h4[2]), bf_hi(h4[2]), bf_lo(h4[3]), bf_hi(h4[3])};
;           y0 += acc[ai][bj][m][0] * s; y1 += acc[ai][bj][m][1] * s;
;           *(u32x4*)(XB + o) = pack8(y0, y1);
; #pragma unroll
;           for (int i = 0; i < 4; ++i) ss += y0[i] * y0[i] + y1[i] * y1[i];
;         }
;         ss += __shfl_xor(ss, 16); ss += __shfl_xor(ss, 32);
;         if (fq == 0) RSS[(size_t)row * 16 + u.pn * 4 + wc] = ss;
.Lxa_11:
	v_and_b32_e32 v129, 64, v219
	v_xor_b32_e32 v128, 16, v219
	v_add_u32_e32 v129, 64, v129
	v_cmp_lt_i32_e32 vcc, v128, v129
	s_lshl_b32 s34, s20, 8
	v_lshl_add_u32 v186, s69, 8, v179
	v_cndmask_b32_e32 v128, v219, v128, vcc
	s_ashr_i32 s35, s34, 31
	v_lshlrev_b32_e32 v205, 2, v128
	v_xor_b32_e32 v128, 32, v219
	v_cmp_lt_i32_e32 vcc, v128, v129
	s_lshl_b64 s[44:45], s[34:35], 1
	v_ashrrev_i32_e32 v187, 31, v186
	v_cndmask_b32_e32 v128, v219, v128, vcc
	v_lshl_add_u64 v[188:189], v[180:181], 0, s[44:45]
	v_lshlrev_b64 v[210:211], 11, v[186:187]
	v_lshlrev_b32_e32 v204, 2, v128
	v_lshl_add_u64 v[128:129], v[188:189], 0, v[210:211]
	global_load_dwordx4 v[206:209], v[128:129], off
	global_load_dwordx4 v[152:155], v[128:129], off offset:256
	v_or_b32_e32 v198, 16, v186
	v_ashrrev_i32_e32 v199, 31, v198
	v_or_b32_e32 v192, 32, v186
	v_lshlrev_b64 v[200:201], 11, v[198:199]
	v_ashrrev_i32_e32 v193, 31, v192
	v_or_b32_e32 v190, 48, v186
	v_lshl_add_u64 v[128:129], v[188:189], 0, v[200:201]
	v_lshlrev_b64 v[196:197], 11, v[192:193]
	v_ashrrev_i32_e32 v191, 31, v190
	global_load_dwordx4 v[148:151], v[128:129], off
	global_load_dwordx4 v[144:147], v[128:129], off offset:256
	v_lshl_add_u64 v[128:129], v[188:189], 0, v[196:197]
	v_lshlrev_b64 v[194:195], 11, v[190:191]
	global_load_dwordx4 v[140:143], v[128:129], off
	global_load_dwordx4 v[136:139], v[128:129], off offset:256
	v_lshl_add_u64 v[128:129], v[188:189], 0, v[194:195]
	global_load_dwordx4 v[132:135], v[128:129], off
	s_nop 0
	global_load_dwordx4 v[128:131], v[128:129], off offset:256
	v_lshl_add_u64 v[210:211], s[94:95], 0, v[210:211]
	s_lshl_b32 s42, s20, 2
	v_lshl_add_u64 v[210:211], v[210:211], 0, s[44:45]
	s_lshl_b32 s20, s6, 1
	v_lshl_add_u64 v[210:211], v[210:211], 0, s[20:21]
	v_lshlrev_b32_e32 v160, 1, v178
	v_lshl_add_u64 v[210:211], v[210:211], 0, v[160:161]
	s_ashr_i32 s43, s42, 31
	s_waitcnt vmcnt(0)
	v_lshlrev_b32_e32 v212, 16, v206
	v_and_b32_e32 v213, 0xffff0000, v206
	v_lshlrev_b32_e32 v206, 16, v207
	v_and_b32_e32 v207, 0xffff0000, v207
	v_lshlrev_b32_e32 v222, 16, v208
	v_and_b32_e32 v223, 0xffff0000, v208
	v_lshlrev_b32_e32 v208, 16, v209
	v_and_b32_e32 v209, 0xffff0000, v209
	v_pk_fma_f32 v[126:127], v[126:127], 0.5, v[206:207] op_sel_hi:[1,0,1]
	v_pk_fma_f32 v[124:125], v[124:125], 0.5, v[212:213] op_sel_hi:[1,0,1]
	v_pk_fma_f32 v[206:207], v[122:123], 0.5, v[208:209] op_sel_hi:[1,0,1]
	v_pk_fma_f32 v[208:209], v[120:121], 0.5, v[222:223] op_sel_hi:[1,0,1]
	v_cvt_pk_bf16_f32 v120, v124, v125
	v_cvt_pk_bf16_f32 v121, v126, v127
	v_cvt_pk_bf16_f32 v122, v208, v209
	v_cvt_pk_bf16_f32 v123, v206, v207
	global_store_dwordx4 v[210:211], v[120:123], off
	s_nop 1
	v_mul_f32_e32 v120, v208, v208
	v_mul_f32_e32 v121, v209, v209
	v_fmac_f32_e32 v120, v124, v124
	v_fmac_f32_e32 v121, v125, v125
	v_add_f32_e32 v120, v120, v121
	v_mul_f32_e32 v121, v206, v206
	v_fmac_f32_e32 v121, v126, v126
	v_add_f32_e32 v120, v121, v120
	v_mul_f32_e32 v121, v207, v207
	v_fmac_f32_e32 v121, v127, v127
	v_add_f32_e32 v206, v121, v120
	v_lshlrev_b32_e32 v120, 16, v152
	v_and_b32_e32 v121, 0xffff0000, v152
	v_lshlrev_b32_e32 v122, 16, v153
	v_and_b32_e32 v123, 0xffff0000, v153
	v_lshlrev_b32_e32 v124, 16, v154
	v_and_b32_e32 v125, 0xffff0000, v154
	v_lshlrev_b32_e32 v126, 16, v155
	v_and_b32_e32 v127, 0xffff0000, v155
	v_pk_fma_f32 v[118:119], v[118:119], 0.5, v[122:123] op_sel_hi:[1,0,1]
	v_pk_fma_f32 v[116:117], v[116:117], 0.5, v[120:121] op_sel_hi:[1,0,1]
	v_pk_fma_f32 v[120:121], v[114:115], 0.5, v[126:127] op_sel_hi:[1,0,1]
	v_pk_fma_f32 v[122:123], v[112:113], 0.5, v[124:125] op_sel_hi:[1,0,1]
	v_cvt_pk_bf16_f32 v112, v116, v117
	v_cvt_pk_bf16_f32 v113, v118, v119
	v_cvt_pk_bf16_f32 v114, v122, v123
	v_cvt_pk_bf16_f32 v115, v120, v121
	global_store_dwordx4 v[210:211], v[112:115], off offset:256
	s_nop 1
	v_mul_f32_e32 v112, v122, v122
	v_fmac_f32_e32 v112, v116, v116
	v_mul_f32_e32 v113, v123, v123
	v_add_f32_e32 v112, v112, v206
	v_fmac_f32_e32 v113, v117, v117
	v_add_f32_e32 v112, v113, v112
	v_mul_f32_e32 v113, v120, v120
	v_fmac_f32_e32 v113, v118, v118
	v_add_f32_e32 v112, v113, v112
	v_mul_f32_e32 v113, v121, v121
	v_fmac_f32_e32 v113, v119, v119
	v_add_f32_e32 v112, v113, v112
	v_mov_b32_e32 v113, v112
	s_nop 1
	v_permlane16_swap_b32_e32 v112, v113
	s_waitcnt lgkmcnt(0)
	v_add_f32_e32 v112, v112, v113
	v_mov_b32_e32 v113, v112
	s_nop 1
	v_permlane32_swap_b32_e32 v112, v113
	s_and_saveexec_b64 s[44:45], s[36:37]
	s_cbranch_execz .LBB0_1218
	v_lshlrev_b64 v[114:115], 6, v[186:187]
	v_lshl_add_u64 v[114:115], s[92:93], 0, v[114:115]
	v_lshl_add_u64 v[114:115], s[42:43], 2, v[114:115]
	s_lshl_b32 s48, s71, 2
	s_mov_b32 s49, s21
	v_lshl_add_u64 v[114:115], v[114:115], 0, s[48:49]
	s_waitcnt lgkmcnt(0)
	v_add_f32_e32 v112, v112, v113
	global_store_dword v[114:115], v112, off
; __device__ __forceinline__ float bf_lo(unsigned u) { return __uint_as_float(u << 16); }
; __device__ __forceinline__ float bf_hi(unsigned u) { return __uint_as_float(u & 0xffff0000u); }
; __device__ __forceinline__ u32x4 pack8(f32x4 a, f32x4 b) { u32x4 o; o[0] = cvt_pk_bf16(a[0], a[1]); o[1] = cvt_pk_bf16(a[2], a[3]); o[2] = cvt_pk_bf16(b[0], b[1]); o[3] = cvt_pk_bf16(b[2], b[3]); return o; }
;   __device__ __forceinline__ void operator()(const AccT& acc, const Unit& u, int ui, int wr, int wc, int fr, int fq) const {
;     ...
;       for (int m = 0; m < 4; ++m) {
;         const int row = u.pm * 256 + ai * 128 + wr * 64 + m * 16 + fr; float ss = 0.f;
; #pragma unroll
;         for (int bj = 0; bj < 2; ++bj) {
;           const size_t o = (size_t)row * DM + u.pn * 256 + bj * 128 + wc * 32 + fq * 8;
;           const u32x4 h4 = xh[m][bj];
;           f32x4 y0 = {bf_lo(h4[0]), bf_hi(h4[0]), bf_lo(h4[1]), bf_hi(h4[1])}, y1 = {bf_lo(h4[2]), bf_hi(h4[2]), bf_lo(h4[3]), bf_hi(h4[3])};
;           y0 += acc[ai][bj][m][0] * s; y1 += acc[ai][bj][m][1] * s;
;           *(u32x4*)(XB + o) = pack8(y0, y1);
; #pragma unroll
;           for (int i = 0; i < 4; ++i) ss += y0[i] * y0[i] + y1[i] * y1[i];
;         }
;         ss += __shfl_xor(ss, 16); ss += __shfl_xor(ss, 32);
;         if (fq == 0) RSS[(size_t)row * 16 + u.pn * 4 + wc] = ss;
.LBB0_1218:
	s_or_b64 exec, exec, s[44:45]
	v_lshlrev_b32_e32 v114, 16, v149
	v_and_b32_e32 v115, 0xffff0000, v149
	v_lshlrev_b32_e32 v116, 16, v150
	v_and_b32_e32 v117, 0xffff0000, v150
	v_lshlrev_b32_e32 v112, 16, v148
	s_waitcnt lgkmcnt(0)
	v_and_b32_e32 v113, 0xffff0000, v148
	v_lshlrev_b32_e32 v118, 16, v151
	v_and_b32_e32 v119, 0xffff0000, v151
	v_pk_fma_f32 v[110:111], v[110:111], 0.5, v[114:115] op_sel_hi:[1,0,1]
	v_pk_fma_f32 v[114:115], v[104:105], 0.5, v[116:117] op_sel_hi:[1,0,1]
	v_pk_fma_f32 v[108:109], v[108:109], 0.5, v[112:113] op_sel_hi:[1,0,1]
	v_pk_fma_f32 v[112:113], v[106:107], 0.5, v[118:119] op_sel_hi:[1,0,1]
	v_cvt_pk_bf16_f32 v106, v114, v115
	v_mul_f32_e32 v114, v114, v114
	v_cvt_pk_bf16_f32 v104, v108, v109
	v_fmac_f32_e32 v114, v108, v108
	v_mul_f32_e32 v108, v115, v115
	v_fmac_f32_e32 v108, v109, v109
	v_mul_f32_e32 v109, v112, v112
	v_add_f32_e32 v108, v114, v108
	v_fmac_f32_e32 v109, v110, v110
	v_add_f32_e32 v108, v109, v108
	v_mul_f32_e32 v109, v113, v113
	v_cvt_pk_bf16_f32 v105, v110, v111
	v_cvt_pk_bf16_f32 v107, v112, v113
	v_fmac_f32_e32 v109, v111, v111
	v_lshlrev_b32_e32 v110, 16, v145
	v_and_b32_e32 v111, 0xffff0000, v145
	v_lshlrev_b32_e32 v112, 16, v146
	v_and_b32_e32 v113, 0xffff0000, v146
	v_add_f32_e32 v118, v109, v108
	v_lshlrev_b32_e32 v108, 16, v144
	v_and_b32_e32 v109, 0xffff0000, v144
	v_pk_fma_f32 v[102:103], v[102:103], 0.5, v[110:111] op_sel_hi:[1,0,1]
	v_pk_fma_f32 v[110:111], v[96:97], 0.5, v[112:113] op_sel_hi:[1,0,1]
	v_pk_fma_f32 v[100:101], v[100:101], 0.5, v[108:109] op_sel_hi:[1,0,1]
	v_mul_f32_e32 v96, v110, v110
	v_lshlrev_b32_e32 v114, 16, v147
	v_and_b32_e32 v115, 0xffff0000, v147
	v_fmac_f32_e32 v96, v100, v100
	v_mul_f32_e32 v97, v111, v111
	v_pk_fma_f32 v[108:109], v[98:99], 0.5, v[114:115] op_sel_hi:[1,0,1]
	v_add_f32_e32 v96, v96, v118
	v_fmac_f32_e32 v97, v101, v101
	v_add_f32_e32 v96, v97, v96
	v_mul_f32_e32 v97, v108, v108
	v_fmac_f32_e32 v97, v102, v102
	v_add_f32_e32 v96, v97, v96
	v_mul_f32_e32 v97, v109, v109
	v_fmac_f32_e32 v97, v103, v103
	v_add_f32_e32 v99, v97, v96
	v_mov_b32_e32 v114, v99
	s_nop 1
	v_permlane16_swap_b32_e32 v99, v114
	v_lshl_add_u64 v[116:117], s[94:95], 0, v[200:201]
	v_lshl_add_u64 v[116:117], s[34:35], 1, v[116:117]
	v_lshl_add_u64 v[96:97], v[116:117], 0, s[20:21]
	v_lshl_add_u64 v[112:113], v[96:97], 0, v[160:161]
	s_waitcnt lgkmcnt(0)
	v_add_f32_e32 v96, v99, v114
	v_mov_b32_e32 v97, v96
	s_nop 1
	v_permlane32_swap_b32_e32 v96, v97
	v_cvt_pk_bf16_f32 v98, v100, v101
	v_cvt_pk_bf16_f32 v99, v102, v103
	v_cvt_pk_bf16_f32 v100, v110, v111
	v_cvt_pk_bf16_f32 v101, v108, v109
	global_store_dwordx4 v[112:113], v[104:107], off
	global_store_dwordx4 v[112:113], v[98:101], off offset:256
	s_and_saveexec_b64 s[44:45], s[36:37]
	s_cbranch_execz .LBB0_1220
	v_lshlrev_b64 v[98:99], 6, v[198:199]
	v_lshl_add_u64 v[98:99], s[92:93], 0, v[98:99]
	v_lshl_add_u64 v[98:99], s[42:43], 2, v[98:99]
	s_lshl_b32 s48, s71, 2
	s_mov_b32 s49, s21
	v_lshl_add_u64 v[98:99], v[98:99], 0, s[48:49]
	s_waitcnt lgkmcnt(0)
	v_add_f32_e32 v96, v96, v97
	global_store_dword v[98:99], v96, off
.LBB0_1220:
	s_or_b64 exec, exec, s[44:45]
	v_lshlrev_b32_e32 v98, 16, v141
	v_and_b32_e32 v99, 0xffff0000, v141
	v_lshlrev_b32_e32 v100, 16, v142
	v_and_b32_e32 v101, 0xffff0000, v142
	v_lshlrev_b32_e32 v96, 16, v140
	s_waitcnt lgkmcnt(0)
	v_and_b32_e32 v97, 0xffff0000, v140
	v_lshlrev_b32_e32 v102, 16, v143
	v_and_b32_e32 v103, 0xffff0000, v143
	v_pk_fma_f32 v[94:95], v[94:95], 0.5, v[98:99] op_sel_hi:[1,0,1]
	v_pk_fma_f32 v[98:99], v[88:89], 0.5, v[100:101] op_sel_hi:[1,0,1]
	v_pk_fma_f32 v[92:93], v[92:93], 0.5, v[96:97] op_sel_hi:[1,0,1]
	v_pk_fma_f32 v[96:97], v[90:91], 0.5, v[102:103] op_sel_hi:[1,0,1]
	v_cvt_pk_bf16_f32 v90, v98, v99
	v_mul_f32_e32 v98, v98, v98
	v_cvt_pk_bf16_f32 v88, v92, v93
	v_fmac_f32_e32 v98, v92, v92
	v_mul_f32_e32 v92, v99, v99
	v_fmac_f32_e32 v92, v93, v93
	v_mul_f32_e32 v93, v96, v96
	v_add_f32_e32 v92, v98, v92
	v_fmac_f32_e32 v93, v94, v94
	v_add_f32_e32 v92, v93, v92
	v_mul_f32_e32 v93, v97, v97
	v_cvt_pk_bf16_f32 v89, v94, v95
	v_cvt_pk_bf16_f32 v91, v96, v97
	v_fmac_f32_e32 v93, v95, v95
	v_lshlrev_b32_e32 v94, 16, v137
	v_and_b32_e32 v95, 0xffff0000, v137
	v_lshlrev_b32_e32 v96, 16, v138
	v_and_b32_e32 v97, 0xffff0000, v138
	v_add_f32_e32 v102, v93, v92
	v_lshlrev_b32_e32 v92, 16, v136
	v_and_b32_e32 v93, 0xffff0000, v136
	v_pk_fma_f32 v[86:87], v[86:87], 0.5, v[94:95] op_sel_hi:[1,0,1]
	v_pk_fma_f32 v[94:95], v[80:81], 0.5, v[96:97] op_sel_hi:[1,0,1]
	v_pk_fma_f32 v[84:85], v[84:85], 0.5, v[92:93] op_sel_hi:[1,0,1]
	v_mul_f32_e32 v80, v94, v94
	v_lshlrev_b32_e32 v98, 16, v139
	v_and_b32_e32 v99, 0xffff0000, v139
	v_fmac_f32_e32 v80, v84, v84
	v_mul_f32_e32 v81, v95, v95
	v_pk_fma_f32 v[92:93], v[82:83], 0.5, v[98:99] op_sel_hi:[1,0,1]
	v_add_f32_e32 v80, v80, v102
	v_fmac_f32_e32 v81, v85, v85
	v_add_f32_e32 v80, v81, v80
	v_mul_f32_e32 v81, v92, v92
	v_fmac_f32_e32 v81, v86, v86
	v_add_f32_e32 v80, v81, v80
	v_mul_f32_e32 v81, v93, v93
	v_fmac_f32_e32 v81, v87, v87
	v_add_f32_e32 v83, v81, v80
	v_mov_b32_e32 v98, v83
	s_nop 1
	v_permlane16_swap_b32_e32 v83, v98
	v_lshl_add_u64 v[100:101], s[94:95], 0, v[196:197]
	v_lshl_add_u64 v[100:101], s[34:35], 1, v[100:101]
	v_lshl_add_u64 v[80:81], v[100:101], 0, s[20:21]
	v_lshl_add_u64 v[96:97], v[80:81], 0, v[160:161]
	s_waitcnt lgkmcnt(0)
	v_add_f32_e32 v80, v83, v98
	v_mov_b32_e32 v81, v80
	s_nop 1
	v_permlane32_swap_b32_e32 v80, v81
	v_cvt_pk_bf16_f32 v82, v84, v85
	v_cvt_pk_bf16_f32 v83, v86, v87
	v_cvt_pk_bf16_f32 v84, v94, v95
	v_cvt_pk_bf16_f32 v85, v92, v93
	global_store_dwordx4 v[96:97], v[88:91], off
	global_store_dwordx4 v[96:97], v[82:85], off offset:256
	s_and_saveexec_b64 s[44:45], s[36:37]
	s_cbranch_execz .LBB0_1222
	v_lshlrev_b64 v[82:83], 6, v[192:193]
	v_lshl_add_u64 v[82:83], s[92:93], 0, v[82:83]
	v_lshl_add_u64 v[82:83], s[42:43], 2, v[82:83]
	s_lshl_b32 s48, s71, 2
	s_mov_b32 s49, s21
	v_lshl_add_u64 v[82:83], v[82:83], 0, s[48:49]
	s_waitcnt lgkmcnt(0)
	v_add_f32_e32 v80, v80, v81
	global_store_dword v[82:83], v80, off
; __device__ __forceinline__ float bf_lo(unsigned u) { return __uint_as_float(u << 16); }
; __device__ __forceinline__ float bf_hi(unsigned u) { return __uint_as_float(u & 0xffff0000u); }
; __device__ __forceinline__ u32x4 pack8(f32x4 a, f32x4 b) { u32x4 o; o[0] = cvt_pk_bf16(a[0], a[1]); o[1] = cvt_pk_bf16(a[2], a[3]); o[2] = cvt_pk_bf16(b[0], b[1]); o[3] = cvt_pk_bf16(b[2], b[3]); return o; }
;   __device__ __forceinline__ void operator()(const AccT& acc, const Unit& u, int ui, int wr, int wc, int fr, int fq) const {
;     ...
;           xh[m][bj] = *(const u32x4*)(XB + (size_t)(u.pm * 256 + ai * 128 + wr * 64 + m * 16 + fr) * DM + u.pn * 256 + bj * 128 + wc * 32 + fq * 8);
; #pragma unroll
;       for (int m = 0; m < 4; ++m) {
;         const int row = u.pm * 256 + ai * 128 + wr * 64 + m * 16 + fr; float ss = 0.f;
; #pragma unroll
;         for (int bj = 0; bj < 2; ++bj) {
;           const size_t o = (size_t)row * DM + u.pn * 256 + bj * 128 + wc * 32 + fq * 8;
;           const u32x4 h4 = xh[m][bj];
;           f32x4 y0 = {bf_lo(h4[0]), bf_hi(h4[0]), bf_lo(h4[1]), bf_hi(h4[1])}, y1 = {bf_lo(h4[2]), bf_hi(h4[2]), bf_lo(h4[3]), bf_hi(h4[3])};
;           y0 += acc[ai][bj][m][0] * s; y1 += acc[ai][bj][m][1] * s;
;           *(u32x4*)(XB + o) = pack8(y0, y1);
; #pragma unroll
;           for (int i = 0; i < 4; ++i) ss += y0[i] * y0[i] + y1[i] * y1[i];
;         }
;         ss += __shfl_xor(ss, 16); ss += __shfl_xor(ss, 32);
;         if (fq == 0) RSS[(size_t)row * 16 + u.pn * 4 + wc] = ss;
.LBB0_1222:
	s_or_b64 exec, exec, s[44:45]
	v_lshlrev_b32_e32 v82, 16, v133
	v_and_b32_e32 v83, 0xffff0000, v133
	v_lshlrev_b32_e32 v84, 16, v134
	v_and_b32_e32 v85, 0xffff0000, v134
	v_lshlrev_b32_e32 v80, 16, v132
	s_waitcnt lgkmcnt(0)
	v_and_b32_e32 v81, 0xffff0000, v132
	v_lshlrev_b32_e32 v86, 16, v135
	v_and_b32_e32 v87, 0xffff0000, v135
	v_pk_fma_f32 v[78:79], v[78:79], 0.5, v[82:83] op_sel_hi:[1,0,1]
	v_pk_fma_f32 v[82:83], v[72:73], 0.5, v[84:85] op_sel_hi:[1,0,1]
	v_pk_fma_f32 v[76:77], v[76:77], 0.5, v[80:81] op_sel_hi:[1,0,1]
	v_pk_fma_f32 v[80:81], v[74:75], 0.5, v[86:87] op_sel_hi:[1,0,1]
	v_cvt_pk_bf16_f32 v74, v82, v83
	v_mul_f32_e32 v82, v82, v82
	v_cvt_pk_bf16_f32 v72, v76, v77
	v_fmac_f32_e32 v82, v76, v76
	v_mul_f32_e32 v76, v83, v83
	v_fmac_f32_e32 v76, v77, v77
	v_mul_f32_e32 v77, v80, v80
	v_add_f32_e32 v76, v82, v76
	v_fmac_f32_e32 v77, v78, v78
	v_add_f32_e32 v76, v77, v76
	v_mul_f32_e32 v77, v81, v81
	v_cvt_pk_bf16_f32 v73, v78, v79
	v_cvt_pk_bf16_f32 v75, v80, v81
	v_fmac_f32_e32 v77, v79, v79
	v_lshlrev_b32_e32 v78, 16, v129
	v_and_b32_e32 v79, 0xffff0000, v129
	v_lshlrev_b32_e32 v80, 16, v130
	v_and_b32_e32 v81, 0xffff0000, v130
	v_add_f32_e32 v86, v77, v76
	v_lshlrev_b32_e32 v76, 16, v128
	v_and_b32_e32 v77, 0xffff0000, v128
	v_pk_fma_f32 v[70:71], v[70:71], 0.5, v[78:79] op_sel_hi:[1,0,1]
	v_pk_fma_f32 v[78:79], v[64:65], 0.5, v[80:81] op_sel_hi:[1,0,1]
	v_pk_fma_f32 v[68:69], v[68:69], 0.5, v[76:77] op_sel_hi:[1,0,1]
	v_mul_f32_e32 v64, v78, v78
	v_lshlrev_b32_e32 v82, 16, v131
	v_and_b32_e32 v83, 0xffff0000, v131
	v_fmac_f32_e32 v64, v68, v68
	v_mul_f32_e32 v65, v79, v79
	v_pk_fma_f32 v[76:77], v[66:67], 0.5, v[82:83] op_sel_hi:[1,0,1]
	v_add_f32_e32 v64, v64, v86
	v_fmac_f32_e32 v65, v69, v69
	v_add_f32_e32 v64, v65, v64
	v_mul_f32_e32 v65, v76, v76
	v_fmac_f32_e32 v65, v70, v70
	v_add_f32_e32 v64, v65, v64
	v_mul_f32_e32 v65, v77, v77
	v_fmac_f32_e32 v65, v71, v71
	v_add_f32_e32 v67, v65, v64
	v_mov_b32_e32 v82, v67
	s_nop 1
	v_permlane16_swap_b32_e32 v67, v82
	v_lshl_add_u64 v[84:85], s[94:95], 0, v[194:195]
	v_lshl_add_u64 v[84:85], s[34:35], 1, v[84:85]
	v_lshl_add_u64 v[64:65], v[84:85], 0, s[20:21]
	v_lshl_add_u64 v[80:81], v[64:65], 0, v[160:161]
	s_waitcnt lgkmcnt(0)
	v_add_f32_e32 v64, v67, v82
	v_mov_b32_e32 v65, v64
	s_nop 1
	v_permlane32_swap_b32_e32 v64, v65
	v_cvt_pk_bf16_f32 v66, v68, v69
	v_cvt_pk_bf16_f32 v67, v70, v71
	v_cvt_pk_bf16_f32 v68, v78, v79
	v_cvt_pk_bf16_f32 v69, v76, v77
	global_store_dwordx4 v[80:81], v[72:75], off
	global_store_dwordx4 v[80:81], v[66:69], off offset:256
	s_and_saveexec_b64 s[44:45], s[36:37]
	s_cbranch_execz .LBB0_1224
	v_lshlrev_b64 v[66:67], 6, v[190:191]
	v_lshl_add_u64 v[66:67], s[92:93], 0, v[66:67]
	v_lshl_add_u64 v[66:67], s[42:43], 2, v[66:67]
	s_lshl_b32 s48, s71, 2
	s_mov_b32 s49, s21
	v_lshl_add_u64 v[66:67], v[66:67], 0, s[48:49]
	s_waitcnt lgkmcnt(0)
	v_add_f32_e32 v64, v64, v65
	global_store_dword v[66:67], v64, off
.LBB0_1224:
	s_or_b64 exec, exec, s[44:45]
	v_add_u32_e32 v104, 0x80, v186
	v_ashrrev_i32_e32 v105, 31, v104
	v_lshlrev_b64 v[110:111], 11, v[104:105]
	s_waitcnt lgkmcnt(0)
	v_lshl_add_u64 v[64:65], v[188:189], 0, v[110:111]
	global_load_dwordx4 v[106:109], v[64:65], off
	global_load_dwordx4 v[88:91], v[64:65], off offset:256
	v_add_u32_e32 v100, 0x90, v186
	v_ashrrev_i32_e32 v101, 31, v100
	v_add_u32_e32 v94, 0xa0, v186
	v_lshlrev_b64 v[102:103], 11, v[100:101]
	v_ashrrev_i32_e32 v95, 31, v94
	v_add_u32_e32 v92, 0xb0, v186
	v_lshl_add_u64 v[64:65], v[188:189], 0, v[102:103]
	v_lshlrev_b64 v[98:99], 11, v[94:95]
	v_ashrrev_i32_e32 v93, 31, v92
	global_load_dwordx4 v[84:87], v[64:65], off
	global_load_dwordx4 v[80:83], v[64:65], off offset:256
	v_lshl_add_u64 v[64:65], v[188:189], 0, v[98:99]
	v_lshlrev_b64 v[96:97], 11, v[92:93]
	global_load_dwordx4 v[76:79], v[64:65], off
	global_load_dwordx4 v[72:75], v[64:65], off offset:256
	v_lshl_add_u64 v[64:65], v[188:189], 0, v[96:97]
	global_load_dwordx4 v[68:71], v[64:65], off
	s_nop 0
	global_load_dwordx4 v[64:67], v[64:65], off offset:256
	v_lshl_add_u64 v[110:111], s[94:95], 0, v[110:111]
	v_lshl_add_u64 v[110:111], s[34:35], 1, v[110:111]
	v_lshl_add_u64 v[110:111], v[110:111], 0, s[20:21]
	v_lshl_add_u64 v[110:111], v[110:111], 0, v[160:161]
	s_waitcnt vmcnt(7)
	v_lshlrev_b32_e32 v112, 16, v106
	v_and_b32_e32 v113, 0xffff0000, v106
	v_lshlrev_b32_e32 v106, 16, v107
	v_and_b32_e32 v107, 0xffff0000, v107
	v_lshlrev_b32_e32 v114, 16, v108
	v_and_b32_e32 v115, 0xffff0000, v108
	v_lshlrev_b32_e32 v108, 16, v109
	v_and_b32_e32 v109, 0xffff0000, v109
	v_pk_fma_f32 v[62:63], v[62:63], 0.5, v[106:107] op_sel_hi:[1,0,1]
	v_pk_fma_f32 v[60:61], v[60:61], 0.5, v[112:113] op_sel_hi:[1,0,1]
	v_pk_fma_f32 v[106:107], v[58:59], 0.5, v[108:109] op_sel_hi:[1,0,1]
	v_pk_fma_f32 v[108:109], v[56:57], 0.5, v[114:115] op_sel_hi:[1,0,1]
	v_cvt_pk_bf16_f32 v56, v60, v61
	v_cvt_pk_bf16_f32 v57, v62, v63
	v_cvt_pk_bf16_f32 v58, v108, v109
	v_cvt_pk_bf16_f32 v59, v106, v107
	global_store_dwordx4 v[110:111], v[56:59], off
	s_nop 1
	v_mul_f32_e32 v56, v108, v108
	v_mul_f32_e32 v57, v109, v109
	v_fmac_f32_e32 v56, v60, v60
	v_fmac_f32_e32 v57, v61, v61
	v_add_f32_e32 v56, v56, v57
	v_mul_f32_e32 v57, v106, v106
	v_fmac_f32_e32 v57, v62, v62
	v_add_f32_e32 v56, v57, v56
	v_mul_f32_e32 v57, v107, v107
	v_fmac_f32_e32 v57, v63, v63
	v_add_f32_e32 v106, v57, v56
	s_waitcnt vmcnt(7)
	v_lshlrev_b32_e32 v56, 16, v88
	v_and_b32_e32 v57, 0xffff0000, v88
	v_lshlrev_b32_e32 v58, 16, v89
	v_and_b32_e32 v59, 0xffff0000, v89
	v_lshlrev_b32_e32 v60, 16, v90
	v_and_b32_e32 v61, 0xffff0000, v90
	v_lshlrev_b32_e32 v62, 16, v91
	v_and_b32_e32 v63, 0xffff0000, v91
	v_pk_fma_f32 v[54:55], v[54:55], 0.5, v[58:59] op_sel_hi:[1,0,1]
	v_pk_fma_f32 v[52:53], v[52:53], 0.5, v[56:57] op_sel_hi:[1,0,1]
	v_pk_fma_f32 v[56:57], v[50:51], 0.5, v[62:63] op_sel_hi:[1,0,1]
	v_pk_fma_f32 v[58:59], v[48:49], 0.5, v[60:61] op_sel_hi:[1,0,1]
	v_cvt_pk_bf16_f32 v48, v52, v53
	v_cvt_pk_bf16_f32 v49, v54, v55
	v_cvt_pk_bf16_f32 v50, v58, v59
	v_cvt_pk_bf16_f32 v51, v56, v57
	global_store_dwordx4 v[110:111], v[48:51], off offset:256
	s_nop 1
	v_mul_f32_e32 v48, v58, v58
	v_fmac_f32_e32 v48, v52, v52
	v_mul_f32_e32 v49, v59, v59
	v_add_f32_e32 v48, v48, v106
	v_fmac_f32_e32 v49, v53, v53
	v_add_f32_e32 v48, v49, v48
	v_mul_f32_e32 v49, v56, v56
	v_fmac_f32_e32 v49, v54, v54
	v_add_f32_e32 v48, v49, v48
	v_mul_f32_e32 v49, v57, v57
	v_fmac_f32_e32 v49, v55, v55
	v_add_f32_e32 v48, v49, v48
	v_mov_b32_e32 v49, v48
	s_nop 1
	v_permlane16_swap_b32_e32 v48, v49
	s_waitcnt lgkmcnt(0)
	v_add_f32_e32 v48, v48, v49
	v_mov_b32_e32 v49, v48
	s_nop 1
	v_permlane32_swap_b32_e32 v48, v49
	s_and_saveexec_b64 s[44:45], s[36:37]
	s_cbranch_execz .LBB0_1226
; __device__ __forceinline__ float bf_lo(unsigned u) { return __uint_as_float(u << 16); }
; __device__ __forceinline__ float bf_hi(unsigned u) { return __uint_as_float(u & 0xffff0000u); }
; __device__ __forceinline__ u32x4 pack8(f32x4 a, f32x4 b) { u32x4 o; o[0] = cvt_pk_bf16(a[0], a[1]); o[1] = cvt_pk_bf16(a[2], a[3]); o[2] = cvt_pk_bf16(b[0], b[1]); o[3] = cvt_pk_bf16(b[2], b[3]); return o; }
;   __device__ __forceinline__ void operator()(const AccT& acc, const Unit& u, int ui, int wr, int wc, int fr, int fq) const {
;     ...
;       for (int m = 0; m < 4; ++m) {
;         const int row = u.pm * 256 + ai * 128 + wr * 64 + m * 16 + fr; float ss = 0.f;
; #pragma unroll
;         for (int bj = 0; bj < 2; ++bj) {
;           const size_t o = (size_t)row * DM + u.pn * 256 + bj * 128 + wc * 32 + fq * 8;
;           const u32x4 h4 = xh[m][bj];
;           f32x4 y0 = {bf_lo(h4[0]), bf_hi(h4[0]), bf_lo(h4[1]), bf_hi(h4[1])}, y1 = {bf_lo(h4[2]), bf_hi(h4[2]), bf_lo(h4[3]), bf_hi(h4[3])};
;           y0 += acc[ai][bj][m][0] * s; y1 += acc[ai][bj][m][1] * s;
;           *(u32x4*)(XB + o) = pack8(y0, y1);
; #pragma unroll
;           for (int i = 0; i < 4; ++i) ss += y0[i] * y0[i] + y1[i] * y1[i];
;         }
;         ss += __shfl_xor(ss, 16); ss += __shfl_xor(ss, 32);
;         if (fq == 0) RSS[(size_t)row * 16 + u.pn * 4 + wc] = ss;
	v_lshlrev_b64 v[50:51], 6, v[104:105]
	v_lshl_add_u64 v[50:51], s[92:93], 0, v[50:51]
	v_lshl_add_u64 v[50:51], s[42:43], 2, v[50:51]
	s_lshl_b32 s48, s71, 2
	s_mov_b32 s49, s21
	v_lshl_add_u64 v[50:51], v[50:51], 0, s[48:49]
	s_waitcnt lgkmcnt(0)
	v_add_f32_e32 v48, v48, v49
	global_store_dword v[50:51], v48, off
.LBB0_1226:
	s_or_b64 exec, exec, s[44:45]
	s_waitcnt vmcnt(7)
	v_lshlrev_b32_e32 v50, 16, v85
	v_and_b32_e32 v51, 0xffff0000, v85
	v_lshlrev_b32_e32 v52, 16, v86
	v_and_b32_e32 v53, 0xffff0000, v86
	v_lshlrev_b32_e32 v48, 16, v84
	s_waitcnt lgkmcnt(0)
	v_and_b32_e32 v49, 0xffff0000, v84
	v_lshlrev_b32_e32 v54, 16, v87
	v_and_b32_e32 v55, 0xffff0000, v87
	v_pk_fma_f32 v[46:47], v[46:47], 0.5, v[50:51] op_sel_hi:[1,0,1]
	v_pk_fma_f32 v[50:51], v[40:41], 0.5, v[52:53] op_sel_hi:[1,0,1]
	v_pk_fma_f32 v[44:45], v[44:45], 0.5, v[48:49] op_sel_hi:[1,0,1]
	v_pk_fma_f32 v[48:49], v[42:43], 0.5, v[54:55] op_sel_hi:[1,0,1]
	v_cvt_pk_bf16_f32 v42, v50, v51
	v_mul_f32_e32 v50, v50, v50
	v_cvt_pk_bf16_f32 v40, v44, v45
	v_fmac_f32_e32 v50, v44, v44
	v_mul_f32_e32 v44, v51, v51
	v_fmac_f32_e32 v44, v45, v45
	v_mul_f32_e32 v45, v48, v48
	v_add_f32_e32 v44, v50, v44
	v_fmac_f32_e32 v45, v46, v46
	v_add_f32_e32 v44, v45, v44
	v_mul_f32_e32 v45, v49, v49
	v_cvt_pk_bf16_f32 v41, v46, v47
	v_cvt_pk_bf16_f32 v43, v48, v49
	v_fmac_f32_e32 v45, v47, v47
	s_waitcnt vmcnt(6)
	v_lshlrev_b32_e32 v46, 16, v81
	v_and_b32_e32 v47, 0xffff0000, v81
	v_lshlrev_b32_e32 v48, 16, v82
	v_and_b32_e32 v49, 0xffff0000, v82
	v_add_f32_e32 v54, v45, v44
	v_lshlrev_b32_e32 v44, 16, v80
	v_and_b32_e32 v45, 0xffff0000, v80
	v_pk_fma_f32 v[38:39], v[38:39], 0.5, v[46:47] op_sel_hi:[1,0,1]
	v_pk_fma_f32 v[46:47], v[32:33], 0.5, v[48:49] op_sel_hi:[1,0,1]
	v_pk_fma_f32 v[36:37], v[36:37], 0.5, v[44:45] op_sel_hi:[1,0,1]
	v_mul_f32_e32 v32, v46, v46
	v_lshlrev_b32_e32 v50, 16, v83
	v_and_b32_e32 v51, 0xffff0000, v83
	v_fmac_f32_e32 v32, v36, v36
	v_mul_f32_e32 v33, v47, v47
	v_pk_fma_f32 v[44:45], v[34:35], 0.5, v[50:51] op_sel_hi:[1,0,1]
	v_add_f32_e32 v32, v32, v54
	v_fmac_f32_e32 v33, v37, v37
	v_add_f32_e32 v32, v33, v32
	v_mul_f32_e32 v33, v44, v44
	v_fmac_f32_e32 v33, v38, v38
	v_add_f32_e32 v32, v33, v32
	v_mul_f32_e32 v33, v45, v45
	v_fmac_f32_e32 v33, v39, v39
	v_add_f32_e32 v35, v33, v32
	v_mov_b32_e32 v50, v35
	s_nop 1
	v_permlane16_swap_b32_e32 v35, v50
	v_lshl_add_u64 v[52:53], s[94:95], 0, v[102:103]
	v_lshl_add_u64 v[52:53], s[34:35], 1, v[52:53]
	v_lshl_add_u64 v[32:33], v[52:53], 0, s[20:21]
	v_lshl_add_u64 v[48:49], v[32:33], 0, v[160:161]
	s_waitcnt lgkmcnt(0)
	v_add_f32_e32 v32, v35, v50
	v_mov_b32_e32 v33, v32
	s_nop 1
	v_permlane32_swap_b32_e32 v32, v33
	v_cvt_pk_bf16_f32 v34, v36, v37
	v_cvt_pk_bf16_f32 v35, v38, v39
	v_cvt_pk_bf16_f32 v36, v46, v47
	v_cvt_pk_bf16_f32 v37, v44, v45
	global_store_dwordx4 v[48:49], v[40:43], off
	global_store_dwordx4 v[48:49], v[34:37], off offset:256
	s_and_saveexec_b64 s[44:45], s[36:37]
	s_cbranch_execz .LBB0_1228
	v_lshlrev_b64 v[34:35], 6, v[100:101]
	v_lshl_add_u64 v[34:35], s[92:93], 0, v[34:35]
	v_lshl_add_u64 v[34:35], s[42:43], 2, v[34:35]
	s_lshl_b32 s48, s71, 2
	s_mov_b32 s49, s21
	v_lshl_add_u64 v[34:35], v[34:35], 0, s[48:49]
	s_waitcnt lgkmcnt(0)
	v_add_f32_e32 v32, v32, v33
	global_store_dword v[34:35], v32, off
; __device__ __forceinline__ float bf_lo(unsigned u) { return __uint_as_float(u << 16); }
; __device__ __forceinline__ float bf_hi(unsigned u) { return __uint_as_float(u & 0xffff0000u); }
; __device__ __forceinline__ u32x4 pack8(f32x4 a, f32x4 b) { u32x4 o; o[0] = cvt_pk_bf16(a[0], a[1]); o[1] = cvt_pk_bf16(a[2], a[3]); o[2] = cvt_pk_bf16(b[0], b[1]); o[3] = cvt_pk_bf16(b[2], b[3]); return o; }
;   __device__ __forceinline__ void operator()(const AccT& acc, const Unit& u, int ui, int wr, int wc, int fr, int fq) const {
;     ...
;       for (int m = 0; m < 4; ++m) {
;         const int row = u.pm * 256 + ai * 128 + wr * 64 + m * 16 + fr; float ss = 0.f;
; #pragma unroll
;         for (int bj = 0; bj < 2; ++bj) {
;           const size_t o = (size_t)row * DM + u.pn * 256 + bj * 128 + wc * 32 + fq * 8;
;           const u32x4 h4 = xh[m][bj];
;           f32x4 y0 = {bf_lo(h4[0]), bf_hi(h4[0]), bf_lo(h4[1]), bf_hi(h4[1])}, y1 = {bf_lo(h4[2]), bf_hi(h4[2]), bf_lo(h4[3]), bf_hi(h4[3])};
;           y0 += acc[ai][bj][m][0] * s; y1 += acc[ai][bj][m][1] * s;
;           *(u32x4*)(XB + o) = pack8(y0, y1);
; #pragma unroll
;           for (int i = 0; i < 4; ++i) ss += y0[i] * y0[i] + y1[i] * y1[i];
;         }
;         ss += __shfl_xor(ss, 16); ss += __shfl_xor(ss, 32);
;         if (fq == 0) RSS[(size_t)row * 16 + u.pn * 4 + wc] = ss;
;       }
.LBB0_1228:
	s_or_b64 exec, exec, s[44:45]
	s_waitcnt vmcnt(7)
	v_lshlrev_b32_e32 v34, 16, v77
	v_and_b32_e32 v35, 0xffff0000, v77
	v_lshlrev_b32_e32 v36, 16, v78
	v_and_b32_e32 v37, 0xffff0000, v78
	v_lshlrev_b32_e32 v32, 16, v76
	s_waitcnt lgkmcnt(0)
	v_and_b32_e32 v33, 0xffff0000, v76
	v_lshlrev_b32_e32 v38, 16, v79
	v_and_b32_e32 v39, 0xffff0000, v79
	v_pk_fma_f32 v[30:31], v[30:31], 0.5, v[34:35] op_sel_hi:[1,0,1]
	v_pk_fma_f32 v[34:35], v[24:25], 0.5, v[36:37] op_sel_hi:[1,0,1]
	v_pk_fma_f32 v[28:29], v[28:29], 0.5, v[32:33] op_sel_hi:[1,0,1]
	v_pk_fma_f32 v[32:33], v[26:27], 0.5, v[38:39] op_sel_hi:[1,0,1]
	v_cvt_pk_bf16_f32 v26, v34, v35
	v_mul_f32_e32 v34, v34, v34
	v_cvt_pk_bf16_f32 v24, v28, v29
	v_fmac_f32_e32 v34, v28, v28
	v_mul_f32_e32 v28, v35, v35
	v_fmac_f32_e32 v28, v29, v29
	v_mul_f32_e32 v29, v32, v32
	v_add_f32_e32 v28, v34, v28
	v_fmac_f32_e32 v29, v30, v30
	v_add_f32_e32 v28, v29, v28
	v_mul_f32_e32 v29, v33, v33
	v_cvt_pk_bf16_f32 v25, v30, v31
	v_cvt_pk_bf16_f32 v27, v32, v33
	v_fmac_f32_e32 v29, v31, v31
	s_waitcnt vmcnt(6)
	v_lshlrev_b32_e32 v30, 16, v73
	v_and_b32_e32 v31, 0xffff0000, v73
	v_lshlrev_b32_e32 v32, 16, v74
	v_and_b32_e32 v33, 0xffff0000, v74
	v_add_f32_e32 v38, v29, v28
	v_lshlrev_b32_e32 v28, 16, v72
	v_and_b32_e32 v29, 0xffff0000, v72
	v_pk_fma_f32 v[22:23], v[22:23], 0.5, v[30:31] op_sel_hi:[1,0,1]
	v_pk_fma_f32 v[30:31], v[16:17], 0.5, v[32:33] op_sel_hi:[1,0,1]
	v_pk_fma_f32 v[20:21], v[20:21], 0.5, v[28:29] op_sel_hi:[1,0,1]
	v_mul_f32_e32 v16, v30, v30
	v_lshlrev_b32_e32 v34, 16, v75
	v_and_b32_e32 v35, 0xffff0000, v75
	v_fmac_f32_e32 v16, v20, v20
	v_mul_f32_e32 v17, v31, v31
	v_pk_fma_f32 v[28:29], v[18:19], 0.5, v[34:35] op_sel_hi:[1,0,1]
	v_add_f32_e32 v16, v16, v38
	v_fmac_f32_e32 v17, v21, v21
	v_add_f32_e32 v16, v17, v16
	v_mul_f32_e32 v17, v28, v28
	v_fmac_f32_e32 v17, v22, v22
	v_add_f32_e32 v16, v17, v16
	v_mul_f32_e32 v17, v29, v29
	v_fmac_f32_e32 v17, v23, v23
	v_add_f32_e32 v19, v17, v16
	v_mov_b32_e32 v34, v19
	s_nop 1
	v_permlane16_swap_b32_e32 v19, v34
	v_lshl_add_u64 v[36:37], s[94:95], 0, v[98:99]
	v_lshl_add_u64 v[36:37], s[34:35], 1, v[36:37]
	v_lshl_add_u64 v[16:17], v[36:37], 0, s[20:21]
	v_lshl_add_u64 v[32:33], v[16:17], 0, v[160:161]
	s_waitcnt lgkmcnt(0)
	v_add_f32_e32 v16, v19, v34
	v_mov_b32_e32 v17, v16
	s_nop 1
	v_permlane32_swap_b32_e32 v16, v17
	v_cvt_pk_bf16_f32 v18, v20, v21
	v_cvt_pk_bf16_f32 v19, v22, v23
	v_cvt_pk_bf16_f32 v20, v30, v31
	v_cvt_pk_bf16_f32 v21, v28, v29
	global_store_dwordx4 v[32:33], v[24:27], off
	global_store_dwordx4 v[32:33], v[18:21], off offset:256
	s_and_saveexec_b64 s[44:45], s[36:37]
	s_cbranch_execz .LBB0_1230
	v_lshlrev_b64 v[18:19], 6, v[94:95]
	v_lshl_add_u64 v[18:19], s[92:93], 0, v[18:19]
	v_lshl_add_u64 v[18:19], s[42:43], 2, v[18:19]
	s_lshl_b32 s48, s71, 2
	s_mov_b32 s49, s21
	v_lshl_add_u64 v[18:19], v[18:19], 0, s[48:49]
	s_waitcnt lgkmcnt(0)
	v_add_f32_e32 v16, v16, v17
	global_store_dword v[18:19], v16, off
.LBB0_1230:
	s_or_b64 exec, exec, s[44:45]
	s_waitcnt vmcnt(7)
	v_lshlrev_b32_e32 v18, 16, v69
	v_and_b32_e32 v19, 0xffff0000, v69
	v_lshlrev_b32_e32 v20, 16, v70
	v_and_b32_e32 v21, 0xffff0000, v70
	v_lshlrev_b32_e32 v16, 16, v68
	s_waitcnt lgkmcnt(0)
	v_and_b32_e32 v17, 0xffff0000, v68
	v_lshlrev_b32_e32 v22, 16, v71
	v_and_b32_e32 v23, 0xffff0000, v71
	v_pk_fma_f32 v[14:15], v[14:15], 0.5, v[18:19] op_sel_hi:[1,0,1]
	v_pk_fma_f32 v[18:19], v[8:9], 0.5, v[20:21] op_sel_hi:[1,0,1]
	v_pk_fma_f32 v[12:13], v[12:13], 0.5, v[16:17] op_sel_hi:[1,0,1]
	v_pk_fma_f32 v[16:17], v[10:11], 0.5, v[22:23] op_sel_hi:[1,0,1]
	v_cvt_pk_bf16_f32 v10, v18, v19
	v_mul_f32_e32 v18, v18, v18
	v_cvt_pk_bf16_f32 v8, v12, v13
	v_fmac_f32_e32 v18, v12, v12
	v_mul_f32_e32 v12, v19, v19
	v_fmac_f32_e32 v12, v13, v13
	v_mul_f32_e32 v13, v16, v16
	v_add_f32_e32 v12, v18, v12
	v_fmac_f32_e32 v13, v14, v14
	v_add_f32_e32 v12, v13, v12
	v_mul_f32_e32 v13, v17, v17
	v_cvt_pk_bf16_f32 v9, v14, v15
	v_cvt_pk_bf16_f32 v11, v16, v17
	v_fmac_f32_e32 v13, v15, v15
	s_waitcnt vmcnt(6)
	v_lshlrev_b32_e32 v14, 16, v65
	v_and_b32_e32 v15, 0xffff0000, v65
	v_lshlrev_b32_e32 v16, 16, v66
	v_and_b32_e32 v17, 0xffff0000, v66
	v_add_f32_e32 v22, v13, v12
	v_lshlrev_b32_e32 v12, 16, v64
	v_and_b32_e32 v13, 0xffff0000, v64
	v_pk_fma_f32 v[6:7], v[6:7], 0.5, v[14:15] op_sel_hi:[1,0,1]
	v_pk_fma_f32 v[14:15], v[0:1], 0.5, v[16:17] op_sel_hi:[1,0,1]
	v_pk_fma_f32 v[4:5], v[4:5], 0.5, v[12:13] op_sel_hi:[1,0,1]
	v_mul_f32_e32 v0, v14, v14
	v_lshlrev_b32_e32 v18, 16, v67
	v_and_b32_e32 v19, 0xffff0000, v67
	v_fmac_f32_e32 v0, v4, v4
	v_mul_f32_e32 v1, v15, v15
	v_pk_fma_f32 v[12:13], v[2:3], 0.5, v[18:19] op_sel_hi:[1,0,1]
	v_add_f32_e32 v0, v0, v22
	v_fmac_f32_e32 v1, v5, v5
	v_add_f32_e32 v0, v1, v0
	v_mul_f32_e32 v1, v12, v12
	v_fmac_f32_e32 v1, v6, v6
	v_add_f32_e32 v0, v1, v0
	v_mul_f32_e32 v1, v13, v13
	v_fmac_f32_e32 v1, v7, v7
	v_add_f32_e32 v3, v1, v0
	v_mov_b32_e32 v18, v3
	s_nop 1
	v_permlane16_swap_b32_e32 v3, v18
	v_lshl_add_u64 v[20:21], s[94:95], 0, v[96:97]
	v_lshl_add_u64 v[20:21], s[34:35], 1, v[20:21]
	v_lshl_add_u64 v[0:1], v[20:21], 0, s[20:21]
	v_lshl_add_u64 v[16:17], v[0:1], 0, v[160:161]
	s_waitcnt lgkmcnt(0)
	v_add_f32_e32 v0, v3, v18
	v_mov_b32_e32 v1, v0
	s_nop 1
	v_permlane32_swap_b32_e32 v0, v1
	v_cvt_pk_bf16_f32 v2, v4, v5
	v_cvt_pk_bf16_f32 v3, v6, v7
	v_cvt_pk_bf16_f32 v4, v14, v15
	v_cvt_pk_bf16_f32 v5, v12, v13
	global_store_dwordx4 v[16:17], v[8:11], off
	global_store_dwordx4 v[16:17], v[2:5], off offset:256
	s_and_saveexec_b64 s[34:35], s[36:37]
	s_cbranch_execz .LBB0_1203
	v_lshlrev_b64 v[2:3], 6, v[92:93]
	v_lshl_add_u64 v[2:3], s[92:93], 0, v[2:3]
	v_lshl_add_u64 v[2:3], s[42:43], 2, v[2:3]
	s_lshl_b32 s20, s71, 2
	v_lshl_add_u64 v[2:3], v[2:3], 0, s[20:21]
	s_waitcnt lgkmcnt(0)
	v_add_f32_e32 v0, v0, v1
	global_store_dword v[2:3], v0, off
	s_branch .LBB0_1203
